# MLA K tile re-layout (conflict-free ds_read_b128 via 128B-row subtiles + xor swizzle) and SWA all-tiles-upfront staging
# speedup vs baseline: 1.0048x; 1.0048x over previous
; #define LAS __attribute__((address_space(3)))
; template <bool MLA> __device__ __forceinline__ void attn_unit(const AttnP& P, int b, int hh, int qb, LAS char* lds) {
;     ...
;     const int tid = threadIdx.x, wid = __builtin_amdgcn_readfirstlane(tid >> 6), lane = tid & 63, r32 = lane & 31, hi = lane >> 5;
;     LAS char* V_lds = lds; LAS char* K_lds = lds + 2 * VBYTES;
;     LAS float* ws = (LAS float*)(lds + 2 * VBYTES + 2 * KBYTES) + wid * 64; LAS float* li_l = ws; LAS float* al_l = ws + 32;
;     LAS float* bias_l = (LAS float*)(lds + 2 * VBYTES + 2 * KBYTES + 2048);
;     const int q0 = qb * 256; const size_t rowbase = (size_t)b * SEQ;
;     const int jt0 = MLA ? 0 : (q0 == 0 ? 0 : -2);
;     const int NT = MLA ? 4 * qb + 4 : 4 - jt0;
;     const int kbase0 = MLA ? 0 : q0 + 64 * jt0;
;     const int qlo = q0 + wid * 32, qm = qlo + r32 - 4 * hi;
;     bf16x8 qr[NQF];
;     const size_t qrow = rowbase + qlo + r32;
;     if constexpr (MLA) {
; #pragma unroll
;         for (int d0 = 0; d0 < 8; ++d0) qr[d0] = *(const bf16x8*)(P.QN + qrow * 2048 + hh * 128 + d0 * 16 + hi * 8);
; #pragma unroll
;         for (int d0 = 0; d0 < 4; ++d0) qr[8 + d0] = *(const bf16x8*)(P.QR + qrow * 1024 + hh * 64 + d0 * 16 + hi * 8);
;     } else {
; #pragma unroll
;         for (int d0 = 0; d0 < 4; ++d0) qr[d0] = *(const bf16x8*)(P.QS + qrow * 2048 + hh * 64 + d0 * 16 + hi * 8);
;         if (tid < 128) bias_l[tid] = P.rel[(int)T5B[tid] * 32 + hh] * (1.0f / SCALE);
;     }
;     bf16x8 sk0, sv0;
;     const int sr8 = tid >> 3, ch8 = tid & 7;
;     const bf16_t* Kg; const bf16_t* Vg; const bf16_t* Rg = nullptr;
;     unsigned okA = 0, okB = 0, orp = 0, ovA = 0, ovB = 0;
;     if constexpr (MLA) {
;         Kg = P.KN + rowbase * 2048 + hh * 128; Vg = P.V + rowbase * 2048 + hh * 128; Rg = P.KR + rowbase * 64;
;         { const int rA = 4 * wid + (lane >> 4), rB = rA + 32, cp = lane & 15; okA = (unsigned)(rA * 2048 + ((cp ^ (rA & 7)) << 3)); okB = (unsigned)(rB * 2048 + ((cp ^ (rB & 7)) << 3)); }
;         { const int rr = 8 * wid + (lane >> 3), cp = lane & 7; orp = (unsigned)(rr * 64 + ((cp ^ (rr & 7)) << 3)); }
;         { const int stA = 2 * wid + (lane >> 5), stB = stA + 16; const int kl = (lane & 31) >> 2, c8 = 8 * (lane & 3);
;           const int kkA = (stA >> 2) * 8 + kl, kkB = (stB >> 2) * 8 + kl;
.LBB0_301:
	s_cmp_lt_i32 s54, 4
	s_cselect_b64 s[4:5], -1, 0
	s_and_b64 s[44:45], s[4:5], s[0:1]
	s_andn2_b64 vcc, exec, s[44:45]
	s_cbranch_vccnz .LBB0_682
	s_cmpk_gt_i32 s2, 0x3ff
	v_lshrrev_b32_e32 v1, 5, v206
	v_and_b32_e32 v198, 7, v162
	v_lshrrev_b32_e32 v200, 2, v162
	v_lshlrev_b32_e32 v147, 3, v162
	v_lshlrev_b32_e32 v199, 1, v162
	v_cmp_gt_u32_e64 s[0:1], 32, v206
	v_and_b32_e32 v151, 1, v162
	s_cbranch_scc1 .LBB0_597
	v_lshlrev_b32_e32 v7, 4, v198
	v_lshlrev_b32_e32 v8, 4, v1
	s_movk_i32 s8, 0x60
	v_lshrrev_b32_e32 v2, 3, v206
	v_xor_b32_e32 v207, v8, v7
	v_bitop3_b32 v208, v8, v7, 32 bitop3:0x36
	v_bitop3_b32 v209, v8, v7, 64 bitop3:0x36
	v_bitop3_b32 v210, v8, v7, s8 bitop3:0x36
	v_and_b32_e32 v254, 31, v162
	v_lshrrev_b32_e32 v3, 3, v254
	v_xor_b32_e32 v3, v3, v254
	v_lshrrev_b32_e32 v254, 2, v254
	v_xor_b32_e32 v254, v254, v3
	v_and_b32_e32 v254, 7, v254
	v_xor_b32_e32 v7, v1, v254
	v_bfe_u32 v5, v162, 3, 5
	v_lshrrev_b32_e32 v6, 3, v5
	v_xor_b32_e32 v6, v6, v5
	v_lshrrev_b32_e32 v5, 2, v5
	v_xor_b32_e32 v5, v5, v6
	v_and_b32_e32 v5, 7, v5
	v_bitop3_b32 v3, v5, v162, 7 bitop3:0x78
	v_lshlrev_b32_e32 v211, 4, v7
	v_bitop3_b32 v7, v1, v254, 2 bitop3:0x36
	v_and_b32_e32 v146, 31, v162
	v_lshrrev_b32_e32 v163, 4, v206
	v_lshlrev_b32_e32 v3, 3, v3
	v_lshrrev_b32_e32 v4, 1, v162
	v_lshlrev_b32_e32 v5, 4, v162
	v_and_b32_e32 v6, 0x118, v147
	s_add_i32 s4, 0, 0x8000
	v_lshlrev_b32_e32 v212, 4, v7
	v_bitop3_b32 v7, v1, v254, 4 bitop3:0x36
	v_mov_b32_e32 v149, 0
	v_and_b32_e32 v4, 8, v4
	v_lshlrev_b32_e32 v202, 2, v1
	v_and_b32_e32 v5, 0xc0, v5
	v_and_or_b32 v6, v199, 32, v6
	v_lshl_add_u32 v204, v146, 7, s4
	s_add_i32 s4, 0, 0xc000
	v_lshlrev_b32_e32 v213, 4, v7
	v_bitop3_b32 v7, v1, v254, 6 bitop3:0x36
	v_lshlrev_b32_e32 v152, 14, v1
	v_lshl_or_b32 v217, v2, 6, v3
	v_lshlrev_b32_e32 v219, 11, v163
	v_mbcnt_lo_u32_b32 v2, -1, 0
	v_lshlrev_b32_e32 v150, 3, v1
	v_and_b32_e32 v201, 15, v162
	v_and_b32_e32 v203, 24, v147
	s_mov_b32 s7, 0
	v_lshl_add_u32 v205, v146, 7, s4
	v_lshlrev_b32_e32 v214, 4, v7
	v_add3_u32 v215, v5, 0, v6
	v_cmp_eq_u32_e64 s[4:5], 0, v151
	v_mov_b32_e32 v153, v149
	v_or_b32_e32 v154, 0x1000, v152
	v_mov_b32_e32 v155, v149
	v_or_b32_e32 v156, 0x2000, v152
	v_mov_b32_e32 v157, v149
	v_or_b32_e32 v158, 0x3000, v152
	v_mov_b32_e32 v159, v149
	v_or_b32_e32 v160, 0x8000, v152
	v_mov_b32_e32 v161, v149
	v_or_b32_e32 v164, 0x9000, v152
	v_mov_b32_e32 v165, v149
	v_or_b32_e32 v166, 0xa000, v152
	v_mov_b32_e32 v167, v149
	v_or_b32_e32 v168, 0xb000, v152
	v_mov_b32_e32 v169, v149
	v_or_b32_e32 v170, 0x10000, v152
	v_mov_b32_e32 v171, v149
	v_or_b32_e32 v172, 0x11000, v152
	v_mov_b32_e32 v173, v149
	v_or_b32_e32 v174, 0x12000, v152
	v_mov_b32_e32 v175, v149
	v_or_b32_e32 v176, 0x13000, v152
	v_mov_b32_e32 v177, v149
	v_or_b32_e32 v178, 0x18000, v152
	v_mov_b32_e32 v179, v149
	v_or_b32_e32 v180, 0x19000, v152
	v_mov_b32_e32 v181, v149
	v_or_b32_e32 v182, 0x1a000, v152
	v_mov_b32_e32 v183, v149
	v_or_b32_e32 v184, 0x1b000, v152
	v_mov_b32_e32 v185, v149
	v_and_or_b32 v216, v200, 3, v4
	v_sub_u32_e32 v218, v146, v202
	v_or_b32_e32 v220, 0x10000, v219
	v_and_b32_e32 v221, 32, v206
	s_mov_b32 s9, 0x4138aa3b
	s_mov_b64 s[46:47], 0x2000
	s_mov_b64 s[48:49], 0x40000
	v_mbcnt_hi_u32_b32 v222, -1, v2
	v_lshlrev_b32_e32 v148, 1, v146
	v_mov_b32_e32 v223, 0xff800000
	s_mov_b32 s12, s2
	s_mov_b32 s13, s2
	s_branch .LBB0_305

; template <bool MLA> __device__ __forceinline__ void attn_unit(const AttnP& P, int b, int hh, int qb, LAS char* lds) {
;     ...
;     bf16x8 qr[NQF];
;     const size_t qrow = rowbase + qlo + r32;
;     if constexpr (MLA) {
; #pragma unroll
;         for (int d0 = 0; d0 < 8; ++d0) qr[d0] = *(const bf16x8*)(P.QN + qrow * 2048 + hh * 128 + d0 * 16 + hi * 8);
; #pragma unroll
;         for (int d0 = 0; d0 < 4; ++d0) qr[8 + d0] = *(const bf16x8*)(P.QR + qrow * 1024 + hh * 64 + d0 * 16 + hi * 8);
;     } else {
; #pragma unroll
;         for (int d0 = 0; d0 < 4; ++d0) qr[d0] = *(const bf16x8*)(P.QS + qrow * 2048 + hh * 64 + d0 * 16 + hi * 8);
;         if (tid < 128) bias_l[tid] = P.rel[(int)T5B[tid] * 32 + hh] * (1.0f / SCALE);
;     }
;     bf16x8 sk0, sv0;
;     const int sr8 = tid >> 3, ch8 = tid & 7;
;     const bf16_t* Kg; const bf16_t* Vg; const bf16_t* Rg = nullptr;
;     unsigned okA = 0, okB = 0, orp = 0, ovA = 0, ovB = 0;
;     if constexpr (MLA) {
;         Kg = P.KN + rowbase * 2048 + hh * 128; Vg = P.V + rowbase * 2048 + hh * 128; Rg = P.KR + rowbase * 64;
;         { const int rA = 4 * wid + (lane >> 4), rB = rA + 32, cp = lane & 15; okA = (unsigned)(rA * 2048 + ((cp ^ (rA & 7)) << 3)); okB = (unsigned)(rB * 2048 + ((cp ^ (rB & 7)) << 3)); }
;         { const int rr = 8 * wid + (lane >> 3), cp = lane & 7; orp = (unsigned)(rr * 64 + ((cp ^ (rr & 7)) << 3)); }
;         { const int stA = 2 * wid + (lane >> 5), stB = stA + 16; const int kl = (lane & 31) >> 2, c8 = 8 * (lane & 3);
;           const int kkA = (stA >> 2) * 8 + kl, kkB = (stB >> 2) * 8 + kl;
;           const int kA = (kkA & ~0xC) | ((kkA & 4) << 1) | ((kkA & 8) >> 1), kB = (kkB & ~0xC) | ((kkB & 4) << 1) | ((kkB & 8) >> 1);
;           ovA = (unsigned)(kA * 2048 + 32 * (stA & 3) + c8); ovB = (unsigned)(kB * 2048 + 32 * (stB & 3) + c8); }
;     } else { Kg = P.KS + (rowbase + sr8) * 256 + (hh >> 3) * 64 + ch8 * 8; Vg = P.VS + (rowbase + sr8) * 256 + (hh >> 3) * 64 + ch8 * 8; }
;     const int kws = KSWZ64(sr8, ch8), vst0 = v_st<NCB>(sr8, ch8 * 8);
;     ...
;     float m_reg = MLA ? 0.f : P.sinks[hh] * (1.0f / SCALE), l_reg = MLA ? 0.f : 1.f;
;     f32x16 o[NCB];
; #pragma unroll
;     for (int d = 0; d < NCB; ++d) o[d] = f32x16{};
;     const int vb0 = (int)(uintptr_t)V_lds + v_rd_base(lane);
;     LOADT(0, 0); asm volatile("s_waitcnt vmcnt(0)" ::: "memory"); WRITET(0); __syncthreads();
.LBB0_305:
	v_readfirstlane_b32 s29, v162
	s_and_b32 s41, s29, 0xffffffc0
	s_and_b32 s14, s13, 31
	s_lshl_b32 s16, s41, 2
	s_ashr_i32 s36, s13, 9
	s_xor_b32 s6, s14, 63
	s_lshr_b32 s40, s29, 6
	s_add_i32 s16, s16, 0
	s_bfe_u32 s15, s13, 0x40005
	s_add_i32 s42, s16, 0x14000
	s_lshl_b32 s16, s6, 8
	s_ashr_i32 s37, s36, 31
	s_lshl_b32 s43, s40, 5
	s_lshl_b32 s70, s15, 8
	s_lshl_b64 s[68:69], s[36:37], 14
	s_lshl_b32 s28, s6, 2
	s_add_i32 s17, s43, s16
	s_add_u32 s76, s68, s17
	s_addc_u32 s77, s69, 0
	v_mov_b32_e32 v3, s77
	v_or_b32_e32 v2, s76, v146
	v_lshlrev_b64 v[4:5], 12, v[2:3]
	v_lshlrev_b64 v[2:3], 11, v[2:3]
	s_mov_b32 s71, s7
	v_lshl_add_u64 v[4:5], s[22:23], 0, v[4:5]
	s_lshl_b32 s6, s15, 7
	s_add_i32 s28, s28, 4
	v_lshl_add_u64 v[2:3], s[20:21], 0, v[2:3]
	s_lshl_b32 s15, s15, 6
	s_lshl_b64 s[72:73], s[36:37], 26
	v_lshl_add_u64 v[4:5], v[4:5], 0, s[70:71]
	v_lshlrev_b32_e32 v186, 1, v150
	v_mov_b32_e32 v187, v149
	v_lshl_add_u64 v[2:3], v[2:3], 0, s[6:7]
	s_add_u32 s33, s61, s72
	v_lshl_add_u64 v[4:5], v[4:5], 0, v[186:187]
	v_lshl_add_u64 v[2:3], v[2:3], 0, v[186:187]
	s_addc_u32 s51, s94, s73
	s_lshl_b32 s50, s40, 2
	global_load_dwordx4 v[98:101], v[4:5], off
	global_load_dwordx4 v[102:105], v[4:5], off offset:32
	global_load_dwordx4 v[106:109], v[4:5], off offset:64
	global_load_dwordx4 v[110:113], v[4:5], off offset:96
	global_load_dwordx4 v[114:117], v[4:5], off offset:128
	global_load_dwordx4 v[118:121], v[4:5], off offset:160
	global_load_dwordx4 v[122:125], v[4:5], off offset:192
	global_load_dwordx4 v[126:129], v[4:5], off offset:224
	global_load_dwordx4 v[130:133], v[2:3], off
	global_load_dwordx4 v[134:137], v[2:3], off offset:32
	global_load_dwordx4 v[138:141], v[2:3], off offset:64
	global_load_dwordx4 v[142:145], v[2:3], off offset:96
	v_lshrrev_b32_e32 v2, 3, v162
	s_lshl_b32 s58, s40, 1
	s_lshr_b32 s59, s29, 4
	s_add_i32 s50, s50, 32
	s_lshr_b32 s29, s29, 5
	s_and_b32 s59, s59, 0xffffff0
	s_and_b32 s62, s50, 0x1ffffff0
	s_and_b32 s63, s29, 4
	s_and_b32 s29, s58, 4
	s_lshl_b64 s[36:37], s[36:37], 21
	s_or_b32 s59, s59, s63
	s_or_b32 s29, s29, s62
	v_or_b32_e32 v5, s29, v216
	s_add_u32 s29, s35, s72
	s_addc_u32 s50, s57, s73
	s_add_u32 s64, s29, s70
	s_addc_u32 s65, s50, 0
	s_add_u32 s50, s33, s70
	v_bfe_u32 v3, v217, 3, 3
	s_addc_u32 s51, s51, 0
	v_lshlrev_b32_e32 v8, 3, v3
	v_or_b32_e32 v3, s58, v1
	s_add_u32 s66, s38, s36
	v_or_b32_e32 v4, s59, v216
	v_lshlrev_b32_e32 v3, 5, v3
	s_addc_u32 s67, s39, s37
	s_lshl_b32 s29, s40, 9
	v_lshlrev_b32_e32 v7, 11, v4
	v_and_b32_e32 v3, 0x60, v3
	v_lshlrev_b32_e32 v5, 11, v5
	v_or_b32_e32 v6, s29, v217
	s_lshl_b32 s29, s40, 10
	v_lshl_or_b32 v2, v2, 11, v8
	v_or3_b32 v9, v7, v3, v203
	v_or3_b32 v10, v5, v3, v203
	s_add_i32 s29, s29, 0
	v_mov_b32_e32 v3, v149
	v_add_u32_e32 v4, 64, v2
	s_add_i32 m0, s29, 0x8000
	v_lshl_add_u64 v[2:3], v[2:3], 1, s[64:65]
	v_mov_b32_e32 v5, v149
	global_load_lds_dwordx4 v[2:3], off
	v_lshl_add_u64 v[2:3], v[4:5], 1, s[64:65]
	s_add_i32 m0, s29, 0xa000
	v_mov_b32_e32 v7, v149
	global_load_lds_dwordx4 v[2:3], off
	v_lshl_add_u64 v[2:3], v[6:7], 1, s[66:67]
	s_add_i32 m0, s29, 0xc000
	s_or_b32 s33, s17, 31
	global_load_lds_dwordx4 v[2:3], off
	v_lshlrev_b32_e32 v2, 1, v9
	v_mov_b32_e32 v3, v149
	v_lshl_add_u64 v[2:3], s[50:51], 0, v[2:3]
	s_mov_b32 m0, s29
	v_mov_b32_e32 v16, v149
	global_load_lds_dwordx4 v[2:3], off
	v_lshlrev_b32_e32 v2, 1, v10
	v_mov_b32_e32 v3, v149
	v_lshl_add_u64 v[2:3], s[50:51], 0, v[2:3]
	s_add_i32 m0, s29, 0x2000
	s_add_u32 s74, s36, 0x13c02000
	global_load_lds_dwordx4 v[2:3], off
	s_addc_u32 s75, s37, 0
	s_or_b32 s36, s72, s70
	s_add_u32 s70, s36, 0x2a040000
	s_addc_u32 s71, s73, 0
	s_lshl_b32 s37, s40, 13
	v_lshrrev_b32_e32 v2, 3, v162
	v_lshlrev_b32_e32 v2, 11, v2
	v_add_u32_e32 v2, v2, v8
	v_mov_b32_e32 v3, v149
	v_lshl_add_u64 v[190:191], v[2:3], 1, s[70:71]
	v_add_u32_e32 v2, 64, v2
	v_lshl_add_u64 v[192:193], v[2:3], 1, s[70:71]
	v_mov_b32_e32 v3, s41
	s_add_u32 s72, s36, 0x32040000
	v_add_lshl_u32 v2, s59, v216, 11
	v_bitop3_b32 v4, v221, s8, v3 bitop3:0xc8
	s_addc_u32 s73, s73, 0
	v_or3_b32 v2, v203, v2, v4
	v_mov_b32_e32 v3, v149
	s_or_b32 s36, s63, s62
	v_lshl_add_u64 v[194:195], v[2:3], 1, s[72:73]
	v_add_lshl_u32 v2, s36, v216, 11
	s_waitcnt vmcnt(0)
	v_or3_b32 v2, v203, v2, v4
	v_mov_b32_e32 v17, v149
	v_lshl_add_u64 v[188:189], v[6:7], 1, s[74:75]
	v_lshl_add_u64 v[196:197], v[2:3], 1, s[72:73]
	v_mov_b32_e32 v2, v149
	v_mov_b32_e32 v4, v149
	v_mov_b32_e32 v6, v149
	v_mov_b32_e32 v8, v149
	v_mov_b32_e32 v9, v149
	v_mov_b32_e32 v10, v149
	v_mov_b32_e32 v11, v149
	v_mov_b32_e32 v12, v149
	v_mov_b32_e32 v13, v149
	v_mov_b32_e32 v14, v149
	v_mov_b32_e32 v15, v149
	s_waitcnt lgkmcnt(0)
	v_mov_b64_e32 v[32:33], v[16:17]
	v_mov_b64_e32 v[48:49], v[16:17]
	v_mov_b64_e32 v[64:65], v[16:17]
	v_lshl_add_u32 v224, v146, 2, s42
	v_lshl_add_u32 v187, v202, 2, s42
	v_add_u32_e32 v225, s43, v218
	s_add_i32 s58, s16, 0x100
	s_mov_b32 s59, 1
	s_mov_b32 s62, s7
	v_mov_b64_e32 v[30:31], v[14:15]
	v_mov_b64_e32 v[28:29], v[12:13]
	v_mov_b64_e32 v[26:27], v[10:11]
	v_mov_b64_e32 v[24:25], v[8:9]
	v_mov_b64_e32 v[22:23], v[6:7]
	v_mov_b64_e32 v[20:21], v[4:5]
	v_mov_b64_e32 v[18:19], v[2:3]
	v_mov_b64_e32 v[46:47], v[14:15]
	v_mov_b64_e32 v[44:45], v[12:13]
	v_mov_b64_e32 v[42:43], v[10:11]
	v_mov_b64_e32 v[40:41], v[8:9]
	v_mov_b64_e32 v[38:39], v[6:7]
	v_mov_b64_e32 v[36:37], v[4:5]
	v_mov_b64_e32 v[34:35], v[2:3]
	v_mov_b64_e32 v[62:63], v[14:15]
	v_mov_b64_e32 v[60:61], v[12:13]
	v_mov_b64_e32 v[58:59], v[10:11]
	v_mov_b64_e32 v[56:57], v[8:9]
	v_mov_b64_e32 v[54:55], v[6:7]
	v_mov_b64_e32 v[52:53], v[4:5]
	v_mov_b64_e32 v[50:51], v[2:3]
	v_mov_b32_e32 v226, 0
	v_mov_b32_e32 v227, 0
	s_waitcnt vmcnt(0)
	s_barrier
	s_branch .LBB0_307

; #define WLK(n) do { asm volatile("s_waitcnt lgkmcnt(" #n ")" ::: "memory"); SBAR(); } while (0)
; #define RDN(S, dd, off) do { const int a_ = rb + (((dd) * 32 + h16) ^ sw); KRD(S##0, a_, off); KRD(S##1, a_, 8192 + (off)); } while (0)
; #define RDR(S, ks) do { const int a_ = rr + (((((ks) * 2 + hi)) ^ (r32 & 7)) << 4); KRD(S##0, a_, 0); KRD(S##1, a_, 4096); } while (0)
; #define MM1(S, d) do { p0 = __builtin_amdgcn_mfma_f32_32x32x16_bf16(S##0, qr[d], p0, 0, 0, 0); p1 = __builtin_amdgcn_mfma_f32_32x32x16_bf16(S##1, qr[d], p1, 0, 0, 0); } while (0)
; __device__ __forceinline__ void qk_mla(f32x16& p0, f32x16& p1, int kaddr, int r32, int hi, const bf16x8* qr) {
;     const int rb = kaddr + r32 * 256, sw = (r32 & 7) << 4, h16 = hi * 16;
;     const int rr = kaddr + 16384 + r32 * 128;
;     ...
;     bf16x8 A0, A1, B0, B1;
;     RDN(A, 0, 0); RDN(B, 1, 0);
;     WLK(2); MM1(A, 0); RDN(A, 2, 0);
;     WLK(2); MM1(B, 1); RDN(B, 3, 0);
;     WLK(2); MM1(A, 2); RDN(A, 0, 128);
;     WLK(2); MM1(B, 3); RDN(B, 1, 128);
;     WLK(2); MM1(A, 4); RDN(A, 2, 128);
;     WLK(2); MM1(B, 5); RDN(B, 3, 128);
;     WLK(2); MM1(A, 6); RDR(A, 0);
;     WLK(2); MM1(B, 7); RDR(B, 1);
;     WLK(2); MM1(A, 8); RDR(A, 2);
;     WLK(2); MM1(B, 9); RDR(B, 3);
;     WLK(2); MM1(A, 10);
;     WLK(0); MM1(B, 11);
; template <bool MLA> __device__ __forceinline__ void attn_unit(const AttnP& P, int b, int hh, int qb, LAS char* lds) {
;     ...
;             f32x16 p0 = f32x16{}, p1 = f32x16{};
;             if constexpr (MLA) {
; #pragma unroll
;                 for (int r = 0; r < 16; ++r) { p0[r] = -m_reg; p1[r] = -m_reg; } }
;             if constexpr (MLA) { qk_mla(p0, p1, (int)(uintptr_t)K_lds + buf * KBYTES, r32, hi, qr); }
.LBB0_311:
	s_mul_i32 s36, s63, 0x6000
	v_add_u32_e32 v244, s36, v204
	v_add_u32_e32 v246, v244, v211
	ds_read_b128 v[228:231], v246 offset:0
	ds_read_b128 v[232:235], v246 offset:0x1000
	v_add_u32_e32 v247, v244, v212
	ds_read_b128 v[236:239], v247 offset:0
	ds_read_b128 v[240:243], v247 offset:0x1000
	s_waitcnt lgkmcnt(2)
	v_xor_b32_e32 v66, 0x80000000, v226
	v_mov_b32_e32 v67, v66
	v_mov_b32_e32 v68, v66
	v_mov_b32_e32 v69, v66
	v_mov_b32_e32 v70, v66
	v_mov_b32_e32 v71, v66
	v_mov_b32_e32 v72, v66
	v_mov_b32_e32 v73, v66
	v_mov_b32_e32 v74, v66
	v_mov_b32_e32 v75, v66
	v_mov_b32_e32 v76, v66
	v_mov_b32_e32 v77, v66
	v_mov_b32_e32 v78, v66
	v_mov_b32_e32 v79, v66
	v_mov_b32_e32 v80, v66
	v_mov_b32_e32 v81, v66
	s_nop 0
	v_mfma_f32_32x32x16_bf16 v[82:97], v[228:231], v[98:101], v[66:81]
	v_add_u32_e32 v248, v244, v213
	ds_read_b128 v[228:231], v248 offset:0
	v_mfma_f32_32x32x16_bf16 v[66:81], v[232:235], v[98:101], v[66:81]
	ds_read_b128 v[232:235], v248 offset:0x1000
	s_waitcnt lgkmcnt(2)
	v_mfma_f32_32x32x16_bf16 v[82:97], v[236:239], v[102:105], v[82:97]
	v_add_u32_e32 v244, v244, v214
	ds_read_b128 v[236:239], v244 offset:0
	v_mfma_f32_32x32x16_bf16 v[66:81], v[240:243], v[102:105], v[66:81]
	ds_read_b128 v[240:243], v244 offset:0x1000
	s_waitcnt lgkmcnt(2)
	v_mfma_f32_32x32x16_bf16 v[82:97], v[228:231], v[106:109], v[82:97]
	ds_read_b128 v[228:231], v246 offset:0x2000
	v_mfma_f32_32x32x16_bf16 v[66:81], v[232:235], v[106:109], v[66:81]
	ds_read_b128 v[232:235], v246 offset:0x3000
	s_waitcnt lgkmcnt(2)
	v_mfma_f32_32x32x16_bf16 v[82:97], v[236:239], v[110:113], v[82:97]
	ds_read_b128 v[236:239], v247 offset:0x2000
	v_mfma_f32_32x32x16_bf16 v[66:81], v[240:243], v[110:113], v[66:81]
	ds_read_b128 v[240:243], v247 offset:0x3000
	s_waitcnt lgkmcnt(2)
	v_mfma_f32_32x32x16_bf16 v[82:97], v[228:231], v[114:117], v[82:97]
	ds_read_b128 v[228:231], v248 offset:0x2000
	v_mfma_f32_32x32x16_bf16 v[66:81], v[232:235], v[114:117], v[66:81]
	ds_read_b128 v[232:235], v248 offset:0x3000
	s_waitcnt lgkmcnt(2)
	v_mfma_f32_32x32x16_bf16 v[82:97], v[236:239], v[118:121], v[82:97]
	ds_read_b128 v[236:239], v244 offset:0x2000
	v_mfma_f32_32x32x16_bf16 v[66:81], v[240:243], v[118:121], v[66:81]
	ds_read_b128 v[240:243], v244 offset:0x3000
	s_waitcnt lgkmcnt(2)
	v_mfma_f32_32x32x16_bf16 v[82:97], v[228:231], v[122:125], v[82:97]
	ds_read_b128 v[228:231], v246 offset:0x4000
	v_mfma_f32_32x32x16_bf16 v[66:81], v[232:235], v[122:125], v[66:81]
	ds_read_b128 v[232:235], v246 offset:0x5000
	s_waitcnt lgkmcnt(2)
	v_mfma_f32_32x32x16_bf16 v[82:97], v[236:239], v[126:129], v[82:97]
	ds_read_b128 v[236:239], v247 offset:0x4000
	v_mfma_f32_32x32x16_bf16 v[66:81], v[240:243], v[126:129], v[66:81]
	ds_read_b128 v[240:243], v247 offset:0x5000
	s_waitcnt lgkmcnt(2)
	v_mfma_f32_32x32x16_bf16 v[82:97], v[228:231], v[130:133], v[82:97]
	ds_read_b128 v[228:231], v248 offset:0x4000
	v_mfma_f32_32x32x16_bf16 v[66:81], v[232:235], v[130:133], v[66:81]
	ds_read_b128 v[232:235], v248 offset:0x5000
	s_waitcnt lgkmcnt(2)
	v_mfma_f32_32x32x16_bf16 v[82:97], v[236:239], v[134:137], v[82:97]
	ds_read_b128 v[236:239], v244 offset:0x4000
	v_mfma_f32_32x32x16_bf16 v[66:81], v[240:243], v[134:137], v[66:81]
	ds_read_b128 v[240:243], v244 offset:0x5000
	s_waitcnt lgkmcnt(2)
	v_mfma_f32_32x32x16_bf16 v[82:97], v[228:231], v[138:141], v[82:97]
	s_waitcnt lgkmcnt(0)
	v_mfma_f32_32x32x16_bf16 v[66:81], v[232:235], v[138:141], v[66:81]
	v_mfma_f32_32x32x16_bf16 v[82:97], v[236:239], v[142:145], v[82:97]
	s_add_i32 s36, s62, 63
	s_cmp_le_u32 s36, s17
	v_mfma_f32_32x32x16_bf16 v[66:81], v[240:243], v[142:145], v[66:81]
	s_cbranch_scc1 .LBB0_313
; __device__ __forceinline__ void mask_tile(f32x16& p0, f32x16& p1, int dq, unsigned W) {
;     const float NEG = -__builtin_inff();
; #pragma unroll
;     for (int r = 0; r < 16; ++r) { const int c = (r & 3) + 8 * (r >> 2);
;         if ((unsigned)(dq - c) >= W) p0[r] = NEG;
;         if ((unsigned)(dq - c - 32) >= W) p1[r] = NEG; }
; }
; template <bool MLA> __device__ __forceinline__ void attn_unit(const AttnP& P, int b, int hh, int qb, LAS char* lds) {
;     ...
;             if (kb + 63 > qlo || (!MLA && kb <= qlo + 31 - W)) mask_tile(p0, p1, dq, (unsigned)W);
	v_add_u32_e32 v228, s16, v225
	v_cmp_gt_u32_e32 vcc, 2.0, v228
	v_subrev_u32_e32 v229, 32, v228
	s_nop 4
	v_cndmask_b32_e32 v82, v223, v82, vcc
	v_cmp_gt_u32_e32 vcc, 2.0, v229
	v_add_u32_e32 v229, -1, v228
	s_nop 0
	v_cndmask_b32_e32 v66, v223, v66, vcc
	v_cmp_gt_u32_e32 vcc, 2.0, v229
	v_subrev_u32_e32 v229, 33, v228
	s_nop 0
	v_cndmask_b32_e32 v83, v223, v83, vcc
	v_cmp_gt_u32_e32 vcc, 2.0, v229
	v_add_u32_e32 v229, -2, v228
	s_nop 0
	v_cndmask_b32_e32 v67, v223, v67, vcc
	v_cmp_gt_u32_e32 vcc, 2.0, v229
	v_subrev_u32_e32 v229, 34, v228
	s_nop 0
	v_cndmask_b32_e32 v84, v223, v84, vcc
	v_cmp_gt_u32_e32 vcc, 2.0, v229
	v_add_u32_e32 v229, -3, v228
	s_nop 0
	v_cndmask_b32_e32 v68, v223, v68, vcc
	v_cmp_gt_u32_e32 vcc, 2.0, v229
	v_subrev_u32_e32 v229, 35, v228
	s_nop 0
	v_cndmask_b32_e32 v85, v223, v85, vcc
	v_cmp_gt_u32_e32 vcc, 2.0, v229
	v_add_u32_e32 v229, -8, v228
	s_nop 0
	v_cndmask_b32_e32 v69, v223, v69, vcc
	v_cmp_gt_u32_e32 vcc, 2.0, v229
	v_subrev_u32_e32 v229, 40, v228
	s_nop 0
	v_cndmask_b32_e32 v86, v223, v86, vcc
	v_cmp_gt_u32_e32 vcc, 2.0, v229
	v_add_u32_e32 v229, -9, v228
	s_nop 0
	v_cndmask_b32_e32 v70, v223, v70, vcc
	v_cmp_gt_u32_e32 vcc, 2.0, v229
	v_subrev_u32_e32 v229, 41, v228
	s_nop 0
	v_cndmask_b32_e32 v87, v223, v87, vcc
	v_cmp_gt_u32_e32 vcc, 2.0, v229
	v_add_u32_e32 v229, -10, v228
	s_nop 0
	v_cndmask_b32_e32 v71, v223, v71, vcc
	v_cmp_gt_u32_e32 vcc, 2.0, v229
	v_subrev_u32_e32 v229, 42, v228
	s_nop 0
	v_cndmask_b32_e32 v88, v223, v88, vcc
	v_cmp_gt_u32_e32 vcc, 2.0, v229
	v_add_u32_e32 v229, -11, v228
	s_nop 0
	v_cndmask_b32_e32 v72, v223, v72, vcc
	v_cmp_gt_u32_e32 vcc, 2.0, v229
	v_subrev_u32_e32 v229, 43, v228
	s_nop 0
	v_cndmask_b32_e32 v89, v223, v89, vcc
	v_cmp_gt_u32_e32 vcc, 2.0, v229
	v_add_u32_e32 v229, -16, v228
	s_nop 0
	v_cndmask_b32_e32 v73, v223, v73, vcc
	v_cmp_gt_u32_e32 vcc, 2.0, v229
	v_subrev_u32_e32 v229, 48, v228
	s_nop 0
	v_cndmask_b32_e32 v90, v223, v90, vcc
	v_cmp_gt_u32_e32 vcc, 2.0, v229
	v_subrev_u32_e32 v229, 17, v228
	s_nop 0
	v_cndmask_b32_e32 v74, v223, v74, vcc
	v_cmp_gt_u32_e32 vcc, 2.0, v229
	v_subrev_u32_e32 v229, 49, v228
	s_nop 0
	v_cndmask_b32_e32 v91, v223, v91, vcc
	v_cmp_gt_u32_e32 vcc, 2.0, v229
	v_subrev_u32_e32 v229, 18, v228
	s_nop 0
	v_cndmask_b32_e32 v75, v223, v75, vcc
	v_cmp_gt_u32_e32 vcc, 2.0, v229
	v_subrev_u32_e32 v229, 50, v228
	s_nop 0
	v_cndmask_b32_e32 v92, v223, v92, vcc
	v_cmp_gt_u32_e32 vcc, 2.0, v229
	v_subrev_u32_e32 v229, 19, v228
	s_nop 0
	v_cndmask_b32_e32 v76, v223, v76, vcc
	v_cmp_gt_u32_e32 vcc, 2.0, v229
	v_subrev_u32_e32 v229, 51, v228
	s_nop 0
	v_cndmask_b32_e32 v93, v223, v93, vcc
	v_cmp_gt_u32_e32 vcc, 2.0, v229
	v_subrev_u32_e32 v229, 24, v228
	s_nop 0
	v_cndmask_b32_e32 v77, v223, v77, vcc
	v_cmp_gt_u32_e32 vcc, 2.0, v229
	v_subrev_u32_e32 v229, 56, v228
	s_nop 0
	v_cndmask_b32_e32 v94, v223, v94, vcc
	v_cmp_gt_u32_e32 vcc, 2.0, v229
	v_subrev_u32_e32 v229, 25, v228
	s_nop 0
	v_cndmask_b32_e32 v78, v223, v78, vcc
	v_cmp_gt_u32_e32 vcc, 2.0, v229
	v_subrev_u32_e32 v229, 57, v228
	s_nop 0
	v_cndmask_b32_e32 v95, v223, v95, vcc
	v_cmp_gt_u32_e32 vcc, 2.0, v229
	v_subrev_u32_e32 v229, 26, v228
	s_nop 0
	v_cndmask_b32_e32 v79, v223, v79, vcc
	v_cmp_gt_u32_e32 vcc, 2.0, v229
	v_subrev_u32_e32 v229, 58, v228
	s_nop 0
	v_cndmask_b32_e32 v96, v223, v96, vcc
	v_cmp_gt_u32_e32 vcc, 2.0, v229
	v_subrev_u32_e32 v229, 27, v228
	v_subrev_u32_e32 v228, 59, v228
	v_cndmask_b32_e32 v80, v223, v80, vcc
	v_cmp_gt_u32_e32 vcc, 2.0, v229
	s_nop 1
	v_cndmask_b32_e32 v97, v223, v97, vcc
	v_cmp_gt_u32_e32 vcc, 2.0, v228
	s_nop 1
	v_cndmask_b32_e32 v81, v223, v81, vcc

; template <bool MLA> __device__ __forceinline__ void attn_unit(const AttnP& P, int b, int hh, int qb, LAS char* lds) {
;     ...
;     bf16x8 qr[NQF];
;     const size_t qrow = rowbase + qlo + r32;
;     if constexpr (MLA) {
; #pragma unroll
;         for (int d0 = 0; d0 < 8; ++d0) qr[d0] = *(const bf16x8*)(P.QN + qrow * 2048 + hh * 128 + d0 * 16 + hi * 8);
; #pragma unroll
;         for (int d0 = 0; d0 < 4; ++d0) qr[8 + d0] = *(const bf16x8*)(P.QR + qrow * 1024 + hh * 64 + d0 * 16 + hi * 8);
;     } else {
; #pragma unroll
;         for (int d0 = 0; d0 < 4; ++d0) qr[d0] = *(const bf16x8*)(P.QS + qrow * 2048 + hh * 64 + d0 * 16 + hi * 8);
;         if (tid < 128) bias_l[tid] = P.rel[(int)T5B[tid] * 32 + hh] * (1.0f / SCALE);
;     }
;     bf16x8 sk0, sv0;
;     const int sr8 = tid >> 3, ch8 = tid & 7;
;     const bf16_t* Kg; const bf16_t* Vg; const bf16_t* Rg = nullptr;
;     unsigned okA = 0, okB = 0, orp = 0, ovA = 0, ovB = 0;
;     if constexpr (MLA) {
;         Kg = P.KN + rowbase * 2048 + hh * 128; Vg = P.V + rowbase * 2048 + hh * 128; Rg = P.KR + rowbase * 64;
;         { const int rA = 4 * wid + (lane >> 4), rB = rA + 32, cp = lane & 15; okA = (unsigned)(rA * 2048 + ((cp ^ (rA & 7)) << 3)); okB = (unsigned)(rB * 2048 + ((cp ^ (rB & 7)) << 3)); }
;         { const int rr = 8 * wid + (lane >> 3), cp = lane & 7; orp = (unsigned)(rr * 64 + ((cp ^ (rr & 7)) << 3)); }
;         { const int stA = 2 * wid + (lane >> 5), stB = stA + 16; const int kl = (lane & 31) >> 2, c8 = 8 * (lane & 3);
;           const int kkA = (stA >> 2) * 8 + kl, kkB = (stB >> 2) * 8 + kl;
;           const int kA = (kkA & ~0xC) | ((kkA & 4) << 1) | ((kkA & 8) >> 1), kB = (kkB & ~0xC) | ((kkB & 4) << 1) | ((kkB & 8) >> 1);
;           ovA = (unsigned)(kA * 2048 + 32 * (stA & 3) + c8); ovB = (unsigned)(kB * 2048 + 32 * (stB & 3) + c8); }
;     } else { Kg = P.KS + (rowbase + sr8) * 256 + (hh >> 3) * 64 + ch8 * 8; Vg = P.VS + (rowbase + sr8) * 256 + (hh >> 3) * 64 + ch8 * 8; }
;     const int kws = KSWZ64(sr8, ch8), vst0 = v_st<NCB>(sr8, ch8 * 8);
;     ...
;     float m_reg = MLA ? 0.f : P.sinks[hh] * (1.0f / SCALE), l_reg = MLA ? 0.f : 1.f;
;     f32x16 o[NCB];
; #pragma unroll
;     for (int d = 0; d < NCB; ++d) o[d] = f32x16{};
;     const int vb0 = (int)(uintptr_t)V_lds + v_rd_base(lane);
;     LOADT(0, 0); asm volatile("s_waitcnt vmcnt(0)" ::: "memory"); WRITET(0); __syncthreads();
.LBB0_451:
	s_or_b64 exec, exec, s[76:77]
	v_readfirstlane_b32 s17, v162
	s_and_b32 s36, s17, 0xffffffc0
	s_lshl_b32 s28, s36, 2
	s_lshr_b32 s33, s17, 6
	s_add_i32 s28, s28, 0
	s_and_b32 s16, s12, 31
	s_add_i32 s37, s28, 0x14000
	s_lshl_b32 s28, s14, 8
	s_lshl_b32 s41, s33, 5
	s_lshl_b32 s16, s16, 8
	s_lshl_b32 s40, s14, 2
	s_add_i32 s14, s41, s28
	s_add_u32 s68, s68, s14
	s_addc_u32 s69, s69, 0
	v_mov_b32_e32 v3, s69
	v_or_b32_e32 v2, s68, v146
	s_waitcnt lgkmcnt(0)
	v_lshlrev_b64 v[4:5], 12, v[2:3]
	v_lshlrev_b64 v[2:3], 11, v[2:3]
	v_lshl_add_u64 v[4:5], s[22:23], 0, v[4:5]
	v_lshl_add_u64 v[2:3], s[20:21], 0, v[2:3]
	s_lshl_b32 s28, s15, 1
	s_mov_b32 s29, s7
	v_lshl_add_u64 v[4:5], v[4:5], 0, s[6:7]
	v_mov_b32_e32 v187, v149
	v_lshl_add_u64 v[2:3], v[2:3], 0, s[28:29]
	v_lshl_add_u64 v[4:5], v[4:5], 0, v[186:187]
	v_lshl_add_u64 v[2:3], v[2:3], 0, v[186:187]
	s_lshl_b32 s15, s33, 2
	s_waitcnt vmcnt(63) expcnt(7) lgkmcnt(15)
	s_barrier
	global_load_dwordx4 v[98:101], v[4:5], off
	global_load_dwordx4 v[102:105], v[4:5], off offset:32
	global_load_dwordx4 v[106:109], v[4:5], off offset:64
	global_load_dwordx4 v[110:113], v[4:5], off offset:96
	global_load_dwordx4 v[114:117], v[4:5], off offset:128
	global_load_dwordx4 v[118:121], v[4:5], off offset:160
	global_load_dwordx4 v[122:125], v[4:5], off offset:192
	global_load_dwordx4 v[126:129], v[4:5], off offset:224
	global_load_dwordx4 v[130:133], v[2:3], off
	global_load_dwordx4 v[134:137], v[2:3], off offset:32
	global_load_dwordx4 v[138:141], v[2:3], off offset:64
	global_load_dwordx4 v[142:145], v[2:3], off offset:96
	v_lshrrev_b32_e32 v2, 3, v162
	s_add_i32 s15, s15, 32
	s_lshl_b32 s28, s33, 1
	s_lshr_b32 s29, s17, 4
	s_and_b32 s42, s15, 0x1ffffff0
	s_lshr_b32 s15, s17, 5
	v_bfe_u32 v3, v217, 3, 3
	s_and_b32 s29, s29, 0xffffff0
	s_and_b32 s43, s15, 4
	s_and_b32 s15, s28, 4
	v_lshlrev_b32_e32 v8, 3, v3
	v_or_b32_e32 v3, s28, v1
	s_or_b32 s58, s29, s43
	s_or_b32 s15, s15, s42
	v_or_b32_e32 v4, s58, v216
	v_or_b32_e32 v5, s15, v216
	v_lshlrev_b32_e32 v3, 5, v3
	s_lshl_b32 s15, s33, 9
	v_lshlrev_b32_e32 v7, 11, v4
	v_and_b32_e32 v3, 0x60, v3
	v_lshlrev_b32_e32 v5, 11, v5
	v_or_b32_e32 v6, s15, v217
	s_lshl_b32 s15, s33, 10
	v_lshl_or_b32 v2, v2, 11, v8
	v_or3_b32 v9, v7, v3, v203
	v_or3_b32 v10, v5, v3, v203
	s_add_i32 s15, s15, 0
	v_mov_b32_e32 v3, v149
	v_add_u32_e32 v4, 64, v2
	s_add_i32 m0, s15, 0x8000
	v_lshl_add_u64 v[2:3], v[2:3], 1, s[64:65]
	v_mov_b32_e32 v5, v149
	global_load_lds_dwordx4 v[2:3], off
	v_lshl_add_u64 v[2:3], v[4:5], 1, s[64:65]
	s_add_i32 m0, s15, 0xa000
	v_mov_b32_e32 v7, v149
	global_load_lds_dwordx4 v[2:3], off
	v_lshl_add_u64 v[2:3], v[6:7], 1, s[66:67]
	s_add_i32 m0, s15, 0xc000
	s_lshl_b32 s33, s33, 13
	global_load_lds_dwordx4 v[2:3], off
	v_lshlrev_b32_e32 v2, 1, v9
	v_mov_b32_e32 v3, v149
	v_lshl_add_u64 v[2:3], s[50:51], 0, v[2:3]
	s_mov_b32 m0, s15
	v_mov_b32_e32 v16, v149
	global_load_lds_dwordx4 v[2:3], off
	v_lshlrev_b32_e32 v2, 1, v10
	v_mov_b32_e32 v3, v149
	v_lshl_add_u64 v[2:3], s[50:51], 0, v[2:3]
	s_add_i32 m0, s15, 0x2000
	v_mov_b32_e32 v17, v149
	global_load_lds_dwordx4 v[2:3], off
	v_lshrrev_b32_e32 v2, 3, v162
	v_lshlrev_b32_e32 v2, 11, v2
	v_add_u32_e32 v2, v2, v8
	v_mov_b32_e32 v3, v149
	v_lshl_add_u64 v[188:189], v[2:3], 1, s[70:71]
	v_add_u32_e32 v2, 64, v2
	v_lshl_add_u64 v[190:191], v[2:3], 1, s[70:71]
	v_mov_b32_e32 v3, s36
	v_add_lshl_u32 v2, s58, v216, 11
	v_bitop3_b32 v4, v221, s8, v3 bitop3:0xc8
	v_or3_b32 v2, v203, v2, v4
	v_mov_b32_e32 v3, v149
	s_or_b32 s33, s43, s42
	v_lshl_add_u64 v[192:193], v[2:3], 1, s[72:73]
	v_add_lshl_u32 v2, s33, v216, 11
	s_waitcnt vmcnt(0)
	v_or3_b32 v2, v203, v2, v4
	v_lshl_add_u64 v[186:187], v[6:7], 1, s[74:75]
	v_lshl_add_u64 v[194:195], v[2:3], 1, s[72:73]
	v_mov_b32_e32 v2, v149
	v_mov_b32_e32 v4, v149
	v_mov_b32_e32 v6, v149
	v_mov_b32_e32 v8, v149
	v_mov_b32_e32 v9, v149
	v_mov_b32_e32 v10, v149
	v_mov_b32_e32 v11, v149
	v_mov_b32_e32 v12, v149
	v_mov_b32_e32 v13, v149
	v_mov_b32_e32 v14, v149
	v_mov_b32_e32 v15, v149
	v_mov_b64_e32 v[32:33], v[16:17]
	v_mov_b64_e32 v[48:49], v[16:17]
	v_mov_b64_e32 v[64:65], v[16:17]
	s_mov_b32 s17, 1
	s_add_i32 s28, s40, 4
	s_or_b32 s29, s14, 31
	v_lshl_add_u32 v224, v146, 2, s37
	v_lshl_add_u32 v197, v202, 2, s37
	v_add_u32_e32 v225, s41, v218
	s_add_i32 s33, s16, 0x100
	s_mov_b32 s58, 0
	v_mov_b32_e32 v226, 0
	v_mov_b64_e32 v[30:31], v[14:15]
	v_mov_b64_e32 v[28:29], v[12:13]
	v_mov_b64_e32 v[26:27], v[10:11]
	v_mov_b64_e32 v[24:25], v[8:9]
	v_mov_b64_e32 v[22:23], v[6:7]
	v_mov_b64_e32 v[20:21], v[4:5]
	v_mov_b64_e32 v[18:19], v[2:3]
	v_mov_b64_e32 v[46:47], v[14:15]
	v_mov_b64_e32 v[44:45], v[12:13]
	v_mov_b64_e32 v[42:43], v[10:11]
	v_mov_b64_e32 v[40:41], v[8:9]
	v_mov_b64_e32 v[38:39], v[6:7]
	v_mov_b64_e32 v[36:37], v[4:5]
	v_mov_b64_e32 v[34:35], v[2:3]
	v_mov_b64_e32 v[62:63], v[14:15]
	v_mov_b64_e32 v[60:61], v[12:13]
	v_mov_b64_e32 v[58:59], v[10:11]
	v_mov_b64_e32 v[56:57], v[8:9]
	v_mov_b64_e32 v[54:55], v[6:7]
	v_mov_b64_e32 v[52:53], v[4:5]
	v_mov_b64_e32 v[50:51], v[2:3]
	v_mov_b32_e32 v227, 0
	s_waitcnt vmcnt(0) lgkmcnt(0)
	s_barrier
	s_branch .LBB0_453

; #define WLK(n) do { asm volatile("s_waitcnt lgkmcnt(" #n ")" ::: "memory"); SBAR(); } while (0)
; #define RDN(S, dd, off) do { const int a_ = rb + (((dd) * 32 + h16) ^ sw); KRD(S##0, a_, off); KRD(S##1, a_, 8192 + (off)); } while (0)
; #define RDR(S, ks) do { const int a_ = rr + (((((ks) * 2 + hi)) ^ (r32 & 7)) << 4); KRD(S##0, a_, 0); KRD(S##1, a_, 4096); } while (0)
; #define MM1(S, d) do { p0 = __builtin_amdgcn_mfma_f32_32x32x16_bf16(S##0, qr[d], p0, 0, 0, 0); p1 = __builtin_amdgcn_mfma_f32_32x32x16_bf16(S##1, qr[d], p1, 0, 0, 0); } while (0)
; __device__ __forceinline__ void qk_mla(f32x16& p0, f32x16& p1, int kaddr, int r32, int hi, const bf16x8* qr) {
;     const int rb = kaddr + r32 * 256, sw = (r32 & 7) << 4, h16 = hi * 16;
;     const int rr = kaddr + 16384 + r32 * 128;
;     ...
;     bf16x8 A0, A1, B0, B1;
;     RDN(A, 0, 0); RDN(B, 1, 0);
;     WLK(2); MM1(A, 0); RDN(A, 2, 0);
;     WLK(2); MM1(B, 1); RDN(B, 3, 0);
;     WLK(2); MM1(A, 2); RDN(A, 0, 128);
;     WLK(2); MM1(B, 3); RDN(B, 1, 128);
;     WLK(2); MM1(A, 4); RDN(A, 2, 128);
;     WLK(2); MM1(B, 5); RDN(B, 3, 128);
;     WLK(2); MM1(A, 6); RDR(A, 0);
;     WLK(2); MM1(B, 7); RDR(B, 1);
;     WLK(2); MM1(A, 8); RDR(A, 2);
;     WLK(2); MM1(B, 9); RDR(B, 3);
;     WLK(2); MM1(A, 10);
;     WLK(0); MM1(B, 11);
; template <bool MLA> __device__ __forceinline__ void attn_unit(const AttnP& P, int b, int hh, int qb, LAS char* lds) {
;     ...
;             f32x16 p0 = f32x16{}, p1 = f32x16{};
;             if constexpr (MLA) {
; #pragma unroll
;                 for (int r = 0; r < 16; ++r) { p0[r] = -m_reg; p1[r] = -m_reg; } }
;             if constexpr (MLA) { qk_mla(p0, p1, (int)(uintptr_t)K_lds + buf * KBYTES, r32, hi, qr); }
.LBB0_457:
	s_mul_i32 s36, s59, 0x6000
	v_add_u32_e32 v248, s36, v204
	v_add_u32_e32 v250, v248, v211
	ds_read_b128 v[228:231], v250 offset:0
	ds_read_b128 v[232:235], v250 offset:0x1000
	v_add_u32_e32 v251, v248, v212
	ds_read_b128 v[236:239], v251 offset:0
	ds_read_b128 v[240:243], v251 offset:0x1000
	s_waitcnt lgkmcnt(2)
	v_xor_b32_e32 v66, 0x80000000, v226
	v_mov_b32_e32 v67, v66
	v_mov_b32_e32 v68, v66
	v_mov_b32_e32 v69, v66
	v_mov_b32_e32 v70, v66
	v_mov_b32_e32 v71, v66
	v_mov_b32_e32 v72, v66
	v_mov_b32_e32 v73, v66
	v_mov_b32_e32 v74, v66
	v_mov_b32_e32 v75, v66
	v_mov_b32_e32 v76, v66
	v_mov_b32_e32 v77, v66
	v_mov_b32_e32 v78, v66
	v_mov_b32_e32 v79, v66
	v_mov_b32_e32 v80, v66
	v_mov_b32_e32 v81, v66
	s_nop 0
	v_mfma_f32_32x32x16_bf16 v[82:97], v[228:231], v[98:101], v[66:81]
	v_add_u32_e32 v252, v248, v213
	ds_read_b128 v[228:231], v252 offset:0
	ds_read_b128 v[244:247], v252 offset:0x1000
	s_waitcnt lgkmcnt(2)
	v_mfma_f32_32x32x16_bf16 v[66:81], v[232:235], v[98:101], v[66:81]
	v_mfma_f32_32x32x16_bf16 v[82:97], v[236:239], v[102:105], v[82:97]
	v_add_u32_e32 v248, v248, v214
	ds_read_b128 v[232:235], v248 offset:0
	ds_read_b128 v[236:239], v248 offset:0x1000
	s_waitcnt lgkmcnt(2)
	v_mfma_f32_32x32x16_bf16 v[66:81], v[240:243], v[102:105], v[66:81]
	v_mfma_f32_32x32x16_bf16 v[82:97], v[228:231], v[106:109], v[82:97]
	ds_read_b128 v[228:231], v250 offset:0x2000
	ds_read_b128 v[240:243], v250 offset:0x3000
	s_waitcnt lgkmcnt(2)
	v_mfma_f32_32x32x16_bf16 v[66:81], v[244:247], v[106:109], v[66:81]
	v_mfma_f32_32x32x16_bf16 v[82:97], v[232:235], v[110:113], v[82:97]
	ds_read_b128 v[232:235], v251 offset:0x2000
	ds_read_b128 v[244:247], v251 offset:0x3000
	s_waitcnt lgkmcnt(2)
	v_mfma_f32_32x32x16_bf16 v[66:81], v[236:239], v[110:113], v[66:81]
	v_mfma_f32_32x32x16_bf16 v[82:97], v[228:231], v[114:117], v[82:97]
	ds_read_b128 v[228:231], v252 offset:0x2000
	ds_read_b128 v[236:239], v252 offset:0x3000
	s_waitcnt lgkmcnt(2)
	v_mfma_f32_32x32x16_bf16 v[66:81], v[240:243], v[114:117], v[66:81]
	v_mfma_f32_32x32x16_bf16 v[82:97], v[232:235], v[118:121], v[82:97]
	ds_read_b128 v[232:235], v248 offset:0x2000
	ds_read_b128 v[240:243], v248 offset:0x3000
	s_waitcnt lgkmcnt(2)
	v_mfma_f32_32x32x16_bf16 v[66:81], v[244:247], v[118:121], v[66:81]
	v_mfma_f32_32x32x16_bf16 v[82:97], v[228:231], v[122:125], v[82:97]
	ds_read_b128 v[228:231], v250 offset:0x4000
	ds_read_b128 v[244:247], v250 offset:0x5000
	s_waitcnt lgkmcnt(2)
	v_mfma_f32_32x32x16_bf16 v[66:81], v[236:239], v[122:125], v[66:81]
	v_mfma_f32_32x32x16_bf16 v[82:97], v[232:235], v[126:129], v[82:97]
	ds_read_b128 v[232:235], v251 offset:0x4000
	ds_read_b128 v[236:239], v251 offset:0x5000
	s_waitcnt lgkmcnt(2)
	v_mfma_f32_32x32x16_bf16 v[66:81], v[240:243], v[126:129], v[66:81]
	v_mfma_f32_32x32x16_bf16 v[82:97], v[228:231], v[130:133], v[82:97]
	ds_read_b128 v[228:231], v252 offset:0x4000
	ds_read_b128 v[240:243], v252 offset:0x5000
	s_waitcnt lgkmcnt(2)
	v_mfma_f32_32x32x16_bf16 v[66:81], v[244:247], v[130:133], v[66:81]
	v_mfma_f32_32x32x16_bf16 v[82:97], v[232:235], v[134:137], v[82:97]
	ds_read_b128 v[232:235], v248 offset:0x4000
	ds_read_b128 v[244:247], v248 offset:0x5000
	s_waitcnt lgkmcnt(2)
	v_mfma_f32_32x32x16_bf16 v[66:81], v[236:239], v[134:137], v[66:81]
	v_mfma_f32_32x32x16_bf16 v[82:97], v[228:231], v[138:141], v[82:97]
	s_waitcnt lgkmcnt(0)
	v_mfma_f32_32x32x16_bf16 v[66:81], v[240:243], v[138:141], v[66:81]
	v_mfma_f32_32x32x16_bf16 v[82:97], v[232:235], v[142:145], v[82:97]
	s_add_i32 s36, s58, 63
	s_cmp_le_u32 s36, s14
	v_mfma_f32_32x32x16_bf16 v[66:81], v[244:247], v[142:145], v[66:81]
	s_cbranch_scc1 .LBB0_459
; __device__ __forceinline__ void mask_tile(f32x16& p0, f32x16& p1, int dq, unsigned W) {
;     const float NEG = -__builtin_inff();
; #pragma unroll
;     for (int r = 0; r < 16; ++r) { const int c = (r & 3) + 8 * (r >> 2);
;         if ((unsigned)(dq - c) >= W) p0[r] = NEG;
;         if ((unsigned)(dq - c - 32) >= W) p1[r] = NEG; }
; }
; template <bool MLA> __device__ __forceinline__ void attn_unit(const AttnP& P, int b, int hh, int qb, LAS char* lds) {
;     ...
;             if (kb + 63 > qlo || (!MLA && kb <= qlo + 31 - W)) mask_tile(p0, p1, dq, (unsigned)W);
	v_add_u32_e32 v228, s16, v225
	v_cmp_gt_u32_e32 vcc, 2.0, v228
	v_subrev_u32_e32 v229, 32, v228
	s_nop 4
	v_cndmask_b32_e32 v82, v223, v82, vcc
	v_cmp_gt_u32_e32 vcc, 2.0, v229
	v_add_u32_e32 v229, -1, v228
	s_nop 0
	v_cndmask_b32_e32 v66, v223, v66, vcc
	v_cmp_gt_u32_e32 vcc, 2.0, v229
	v_subrev_u32_e32 v229, 33, v228
	s_nop 0
	v_cndmask_b32_e32 v83, v223, v83, vcc
	v_cmp_gt_u32_e32 vcc, 2.0, v229
	v_add_u32_e32 v229, -2, v228
	s_nop 0
	v_cndmask_b32_e32 v67, v223, v67, vcc
	v_cmp_gt_u32_e32 vcc, 2.0, v229
	v_subrev_u32_e32 v229, 34, v228
	s_nop 0
	v_cndmask_b32_e32 v84, v223, v84, vcc
	v_cmp_gt_u32_e32 vcc, 2.0, v229
	v_add_u32_e32 v229, -3, v228
	s_nop 0
	v_cndmask_b32_e32 v68, v223, v68, vcc
	v_cmp_gt_u32_e32 vcc, 2.0, v229
	v_subrev_u32_e32 v229, 35, v228
	s_nop 0
	v_cndmask_b32_e32 v85, v223, v85, vcc
	v_cmp_gt_u32_e32 vcc, 2.0, v229
	v_add_u32_e32 v229, -8, v228
	s_nop 0
	v_cndmask_b32_e32 v69, v223, v69, vcc
	v_cmp_gt_u32_e32 vcc, 2.0, v229
	v_subrev_u32_e32 v229, 40, v228
	s_nop 0
	v_cndmask_b32_e32 v86, v223, v86, vcc
	v_cmp_gt_u32_e32 vcc, 2.0, v229
	v_add_u32_e32 v229, -9, v228
	s_nop 0
	v_cndmask_b32_e32 v70, v223, v70, vcc
	v_cmp_gt_u32_e32 vcc, 2.0, v229
	v_subrev_u32_e32 v229, 41, v228
	s_nop 0
	v_cndmask_b32_e32 v87, v223, v87, vcc
	v_cmp_gt_u32_e32 vcc, 2.0, v229
	v_add_u32_e32 v229, -10, v228
	s_nop 0
	v_cndmask_b32_e32 v71, v223, v71, vcc
	v_cmp_gt_u32_e32 vcc, 2.0, v229
	v_subrev_u32_e32 v229, 42, v228
	s_nop 0
	v_cndmask_b32_e32 v88, v223, v88, vcc
	v_cmp_gt_u32_e32 vcc, 2.0, v229
	v_add_u32_e32 v229, -11, v228
	s_nop 0
	v_cndmask_b32_e32 v72, v223, v72, vcc
	v_cmp_gt_u32_e32 vcc, 2.0, v229
	v_subrev_u32_e32 v229, 43, v228
	s_nop 0
	v_cndmask_b32_e32 v89, v223, v89, vcc
	v_cmp_gt_u32_e32 vcc, 2.0, v229
	v_add_u32_e32 v229, -16, v228
	s_nop 0
	v_cndmask_b32_e32 v73, v223, v73, vcc
	v_cmp_gt_u32_e32 vcc, 2.0, v229
	v_subrev_u32_e32 v229, 48, v228
	s_nop 0
	v_cndmask_b32_e32 v90, v223, v90, vcc
	v_cmp_gt_u32_e32 vcc, 2.0, v229
	v_subrev_u32_e32 v229, 17, v228
	s_nop 0
	v_cndmask_b32_e32 v74, v223, v74, vcc
	v_cmp_gt_u32_e32 vcc, 2.0, v229
	v_subrev_u32_e32 v229, 49, v228
	s_nop 0
	v_cndmask_b32_e32 v91, v223, v91, vcc
	v_cmp_gt_u32_e32 vcc, 2.0, v229
	v_subrev_u32_e32 v229, 18, v228
	s_nop 0
	v_cndmask_b32_e32 v75, v223, v75, vcc
	v_cmp_gt_u32_e32 vcc, 2.0, v229
	v_subrev_u32_e32 v229, 50, v228
	s_nop 0
	v_cndmask_b32_e32 v92, v223, v92, vcc
	v_cmp_gt_u32_e32 vcc, 2.0, v229
	v_subrev_u32_e32 v229, 19, v228
	s_nop 0
	v_cndmask_b32_e32 v76, v223, v76, vcc
	v_cmp_gt_u32_e32 vcc, 2.0, v229
	v_subrev_u32_e32 v229, 51, v228
	s_nop 0
	v_cndmask_b32_e32 v93, v223, v93, vcc
	v_cmp_gt_u32_e32 vcc, 2.0, v229
	v_subrev_u32_e32 v229, 24, v228
	s_nop 0
	v_cndmask_b32_e32 v77, v223, v77, vcc
	v_cmp_gt_u32_e32 vcc, 2.0, v229
	v_subrev_u32_e32 v229, 56, v228
	s_nop 0
	v_cndmask_b32_e32 v94, v223, v94, vcc
	v_cmp_gt_u32_e32 vcc, 2.0, v229
	v_subrev_u32_e32 v229, 25, v228
	s_nop 0
	v_cndmask_b32_e32 v78, v223, v78, vcc
	v_cmp_gt_u32_e32 vcc, 2.0, v229
	v_subrev_u32_e32 v229, 57, v228
	s_nop 0
	v_cndmask_b32_e32 v95, v223, v95, vcc
	v_cmp_gt_u32_e32 vcc, 2.0, v229
	v_subrev_u32_e32 v229, 26, v228
	s_nop 0
	v_cndmask_b32_e32 v79, v223, v79, vcc
	v_cmp_gt_u32_e32 vcc, 2.0, v229
	v_subrev_u32_e32 v229, 58, v228
	s_nop 0
	v_cndmask_b32_e32 v96, v223, v96, vcc
	v_cmp_gt_u32_e32 vcc, 2.0, v229
	v_subrev_u32_e32 v229, 27, v228
	v_subrev_u32_e32 v228, 59, v228
	v_cndmask_b32_e32 v80, v223, v80, vcc
	v_cmp_gt_u32_e32 vcc, 2.0, v229
	s_nop 1
	v_cndmask_b32_e32 v97, v223, v97, vcc
	v_cmp_gt_u32_e32 vcc, 2.0, v228
	s_nop 1
	v_cndmask_b32_e32 v81, v223, v81, vcc

; template <int NCB> __device__ __forceinline__ int v_st(int k, int c) { const int kk = (k & ~0xC) | ((k & 4) << 1) | ((k & 8) >> 1); return ((kk >> 3) * NCB + (c >> 5)) * 512 + ((kk & 7) * 32 + (c & 31)) * 2; }
; template <bool MLA> __device__ __forceinline__ void attn_unit(const AttnP& P, int b, int hh, int qb, LAS char* lds) {
;     ...
;         for (int d0 = 0; d0 < 4; ++d0) qr[d0] = *(const bf16x8*)(P.QS + qrow * 2048 + hh * 64 + d0 * 16 + hi * 8);
;         if (tid < 128) bias_l[tid] = P.rel[(int)T5B[tid] * 32 + hh] * (1.0f / SCALE);
;     }
;     bf16x8 sk0, sv0;
;     const int sr8 = tid >> 3, ch8 = tid & 7;
;     const bf16_t* Kg; const bf16_t* Vg; const bf16_t* Rg = nullptr;
;     unsigned okA = 0, okB = 0, orp = 0, ovA = 0, ovB = 0;
;     if constexpr (MLA) {
;         Kg = P.KN + rowbase * 2048 + hh * 128; Vg = P.V + rowbase * 2048 + hh * 128; Rg = P.KR + rowbase * 64;
;         { const int rA = 4 * wid + (lane >> 4), rB = rA + 32, cp = lane & 15; okA = (unsigned)(rA * 2048 + ((cp ^ (rA & 7)) << 3)); okB = (unsigned)(rB * 2048 + ((cp ^ (rB & 7)) << 3)); }
;         { const int rr = 8 * wid + (lane >> 3), cp = lane & 7; orp = (unsigned)(rr * 64 + ((cp ^ (rr & 7)) << 3)); }
;         { const int stA = 2 * wid + (lane >> 5), stB = stA + 16; const int kl = (lane & 31) >> 2, c8 = 8 * (lane & 3);
;           const int kkA = (stA >> 2) * 8 + kl, kkB = (stB >> 2) * 8 + kl;
;           const int kA = (kkA & ~0xC) | ((kkA & 4) << 1) | ((kkA & 8) >> 1), kB = (kkB & ~0xC) | ((kkB & 4) << 1) | ((kkB & 8) >> 1);
;           ovA = (unsigned)(kA * 2048 + 32 * (stA & 3) + c8); ovB = (unsigned)(kB * 2048 + 32 * (stB & 3) + c8); }
;     } else { Kg = P.KS + (rowbase + sr8) * 256 + (hh >> 3) * 64 + ch8 * 8; Vg = P.VS + (rowbase + sr8) * 256 + (hh >> 3) * 64 + ch8 * 8; }
;     const int kws = KSWZ64(sr8, ch8), vst0 = v_st<NCB>(sr8, ch8 * 8);
.LBB0_597:
	v_readlane_b32 s64, v253, 0
	s_cmpk_gt_i32 s2, 0xfff
	v_readlane_b32 s68, v253, 4
	v_readlane_b32 s69, v253, 5
	v_readlane_b32 s70, v253, 6
	v_readlane_b32 s71, v253, 7
	v_readlane_b32 s65, v253, 1
	v_readlane_b32 s66, v253, 2
	v_readlane_b32 s67, v253, 3
	v_readlane_b32 s72, v253, 8
	v_readlane_b32 s73, v253, 9
	v_readlane_b32 s74, v253, 10
	v_readlane_b32 s75, v253, 11
	v_readlane_b32 s76, v253, 12
	v_readlane_b32 s77, v253, 13
	v_readlane_b32 s78, v253, 14
	v_readlane_b32 s79, v253, 15
	s_cbranch_scc1 .LBB0_682
	v_lshrrev_b32_e32 v96, 3, v162
	v_and_b32_e32 v5, 0x70, v96
	v_and_or_b32 v5, v200, 8, v5
	v_xor_b32_e32 v3, v96, v162
	v_lshrrev_b32_e32 v5, 2, v5
	v_bfe_u32 v7, v147, 5, 1
	v_lshlrev_b32_e32 v3, 4, v3
	v_lshrrev_b32_e32 v6, 4, v162
	v_or_b32_e32 v5, v5, v7
	v_bfe_u32 v7, v162, 3, 2
	v_and_b32_e32 v3, 0x70, v3
	v_and_or_b32 v6, v6, 4, v7
	v_lshlrev_b32_e32 v7, 4, v162
	v_lshlrev_b32_e32 v9, 7, v96
	v_lshlrev_b32_e32 v6, 6, v6
	v_and_b32_e32 v8, 48, v7
	v_add3_u32 v140, 0, v3, v9
	v_lshl_add_u32 v3, v5, 9, 0
	v_mov_b32_e32 v93, 0
	v_add3_u32 v141, v3, v6, v8
	v_bitop3_b32 v6, v1, v162, 7 bitop3:0x78
	v_mov_b32_e32 v163, v93
	s_getpc_b64 s[4:5]
	s_add_u32 s4, s4, _ZN3attL3T5BE@rel32@lo+4
	s_addc_u32 s5, s5, _ZN3attL3T5BE@rel32@hi+12
	v_lshlrev_b32_e32 v143, 4, v6
	v_bitop3_b32 v6, v1, v198, 2 bitop3:0x36
	v_and_b32_e32 v90, 31, v162
	v_lshlrev_b32_e32 v2, 3, v1
	v_lshlrev_b32_e32 v91, 2, v1
	v_lshl_add_u64 v[94:95], s[4:5], 0, v[162:163]
	v_and_b32_e32 v3, 32, v199
	v_lshlrev_b32_e32 v144, 4, v6
	v_bitop3_b32 v6, v1, v198, 4 bitop3:0x36
	s_movk_i32 s4, 0x118
	s_movk_i32 s8, 0x80
	v_and_b32_e32 v4, 56, v147
	v_and_b32_e32 v5, 0xc0, v7
	v_lshlrev_b32_e32 v145, 4, v6
	v_bitop3_b32 v6, v1, v198, 6 bitop3:0x36
	v_and_or_b32 v3, v147, s4, v3
	v_lshlrev_b32_e32 v98, 14, v1
	v_sub_u32_e32 v1, v90, v91
	v_lshlrev_b32_e32 v92, 1, v2
	v_mbcnt_lo_u32_b32 v2, -1, 0
	v_readlane_b32 s42, v253, 44
	v_readlane_b32 s58, v253, 46
	v_cmp_gt_u32_e64 s[0:1], s8, v162
	s_mov_b32 s39, 0
	v_lshl_add_u32 v97, v162, 2, 0
	v_lshl_add_u32 v142, v90, 7, 0
	v_lshlrev_b32_e32 v146, 4, v6
	v_cmp_gt_u32_e64 s[6:7], 32, v206
	v_add3_u32 v147, v5, 0, v3
	v_cmp_eq_u32_e64 s[4:5], 0, v151
	v_mov_b32_e32 v99, v93
	v_or_b32_e32 v100, 0x1000, v98
	v_mov_b32_e32 v101, v93
	v_or_b32_e32 v102, 0x2000, v98
	v_mov_b32_e32 v103, v93
	v_or_b32_e32 v104, 0x3000, v98
	v_mov_b32_e32 v105, v93
	v_or_b32_e32 v106, 0x8000, v98
	v_mov_b32_e32 v107, v93
	v_or_b32_e32 v108, 0x9000, v98
	v_mov_b32_e32 v109, v93
	v_or_b32_e32 v110, 0xa000, v98
	v_mov_b32_e32 v111, v93
	v_or_b32_e32 v112, 0xb000, v98
	v_mov_b32_e32 v113, v93
	v_or_b32_e32 v114, 0x10000, v98
	v_mov_b32_e32 v115, v93
	v_or_b32_e32 v116, 0x11000, v98
	v_mov_b32_e32 v117, v93
	v_or_b32_e32 v118, 0x12000, v98
	v_mov_b32_e32 v119, v93
	v_or_b32_e32 v120, 0x13000, v98
	v_mov_b32_e32 v121, v93
	v_or_b32_e32 v122, 0x18000, v98
	v_mov_b32_e32 v123, v93
	v_or_b32_e32 v124, 0x19000, v98
	v_mov_b32_e32 v125, v93
	v_or_b32_e32 v126, 0x1a000, v98
	v_mov_b32_e32 v127, v93
	v_or_b32_e32 v128, 0x1b000, v98
	v_mov_b32_e32 v129, v93
	v_subrev_u32_e32 v1, 59, v1
	s_mov_b32 s9, 0x41000000
	v_lshlrev_b32_e32 v130, 1, v90
	v_lshlrev_b32_e32 v132, 1, v4
	v_mov_b32_e32 v148, 0xff800000
	v_mbcnt_hi_u32_b32 v149, -1, v2
	s_mov_b32 s12, s2
	v_readlane_b32 s43, v253, 45
	v_readlane_b32 s59, v253, 47
	s_mov_b64 s[98:99], 0x8000
	s_and_saveexec_b64 s[50:51], s[0:1]
	global_load_ubyte v207, v[94:95], off
	s_or_b64 exec, exec, s[50:51]
	s_waitcnt vmcnt(0)
	s_branch .LBB0_600

; template <int NCB> __device__ __forceinline__ int v_st(int k, int c) { const int kk = (k & ~0xC) | ((k & 4) << 1) | ((k & 8) >> 1); return ((kk >> 3) * NCB + (c >> 5)) * 512 + ((kk & 7) * 32 + (c & 31)) * 2; }
; template <bool MLA> __device__ __forceinline__ void attn_unit(const AttnP& P, int b, int hh, int qb, LAS char* lds) {
;     ...
;         for (int d0 = 0; d0 < 4; ++d0) qr[d0] = *(const bf16x8*)(P.QS + qrow * 2048 + hh * 64 + d0 * 16 + hi * 8);
;         if (tid < 128) bias_l[tid] = P.rel[(int)T5B[tid] * 32 + hh] * (1.0f / SCALE);
;     }
;     bf16x8 sk0, sv0;
;     const int sr8 = tid >> 3, ch8 = tid & 7;
;     const bf16_t* Kg; const bf16_t* Vg; const bf16_t* Rg = nullptr;
;     unsigned okA = 0, okB = 0, orp = 0, ovA = 0, ovB = 0;
;     if constexpr (MLA) {
;         Kg = P.KN + rowbase * 2048 + hh * 128; Vg = P.V + rowbase * 2048 + hh * 128; Rg = P.KR + rowbase * 64;
;         { const int rA = 4 * wid + (lane >> 4), rB = rA + 32, cp = lane & 15; okA = (unsigned)(rA * 2048 + ((cp ^ (rA & 7)) << 3)); okB = (unsigned)(rB * 2048 + ((cp ^ (rB & 7)) << 3)); }
;         { const int rr = 8 * wid + (lane >> 3), cp = lane & 7; orp = (unsigned)(rr * 64 + ((cp ^ (rr & 7)) << 3)); }
;         { const int stA = 2 * wid + (lane >> 5), stB = stA + 16; const int kl = (lane & 31) >> 2, c8 = 8 * (lane & 3);
;           const int kkA = (stA >> 2) * 8 + kl, kkB = (stB >> 2) * 8 + kl;
;           const int kA = (kkA & ~0xC) | ((kkA & 4) << 1) | ((kkA & 8) >> 1), kB = (kkB & ~0xC) | ((kkB & 4) << 1) | ((kkB & 8) >> 1);
;           ovA = (unsigned)(kA * 2048 + 32 * (stA & 3) + c8); ovB = (unsigned)(kB * 2048 + 32 * (stB & 3) + c8); }
;     } else { Kg = P.KS + (rowbase + sr8) * 256 + (hh >> 3) * 64 + ch8 * 8; Vg = P.VS + (rowbase + sr8) * 256 + (hh >> 3) * 64 + ch8 * 8; }
;     const int kws = KSWZ64(sr8, ch8), vst0 = v_st<NCB>(sr8, ch8 * 8);
;     ...
;     float m_reg = MLA ? 0.f : P.sinks[hh] * (1.0f / SCALE), l_reg = MLA ? 0.f : 1.f;
;     f32x16 o[NCB];
; #pragma unroll
;     for (int d = 0; d < NCB; ++d) o[d] = f32x16{};
;     const int vb0 = (int)(uintptr_t)V_lds + v_rd_base(lane);
;     LOADT(0, 0); asm volatile("s_waitcnt vmcnt(0)" ::: "memory"); WRITET(0); __syncthreads();
;     for (int t = 0; t < NT; ++t) {
;         const int buf = t & 1;
;         if (t + 1 < NT) LOADT(t + 1, buf ^ 1);
.LBB0_600:
	v_readfirstlane_b32 s29, v162
	s_and_b32 s17, s2, 63
	s_ashr_i32 s36, s2, 11
	s_lshr_b32 s13, s29, 1
	s_lshl_b32 s28, s17, 8
	s_ashr_i32 s37, s36, 31
	s_and_b32 s16, s13, 0x7fffffe0
	s_bfe_u32 s15, s2, 0x50006
	s_lshl_b64 s[48:49], s[36:37], 14
	s_add_i32 s13, s16, s28
	s_add_u32 s46, s48, s13
	s_addc_u32 s47, s49, 0
	v_mov_b32_e32 v3, s47
	v_or_b32_e32 v2, s46, v90
	v_lshlrev_b64 v[2:3], 12, v[2:3]
	v_lshl_add_u64 v[2:3], s[18:19], 0, v[2:3]
	s_lshl_b32 s38, s15, 7
	v_lshl_add_u64 v[2:3], v[2:3], 0, s[38:39]
	v_lshl_add_u64 v[2:3], v[2:3], 0, v[92:93]
	global_load_dwordx4 v[66:69], v[2:3], off
	global_load_dwordx4 v[70:73], v[2:3], off offset:32
	global_load_dwordx4 v[74:77], v[2:3], off offset:64
	global_load_dwordx4 v[78:81], v[2:3], off offset:96
	s_lshl_b32 s14, s15, 6
	s_and_saveexec_b64 s[50:51], s[0:1]
	s_cbranch_execz .LBB0_602
	s_lshl_b32 s33, s15, 2
	v_lshl_or_b32 v2, v207, 7, s33
	global_load_dword v204, v2, s[70:71]
.LBB0_602:
	s_or_b64 exec, exec, s[50:51]
	s_and_b32 s29, s29, 0x3fffffc0
	s_and_b32 s35, s12, 63
	s_lshl_b32 s29, s29, 2
	s_lshr_b32 s33, s2, 6
	s_lshl_b32 s35, s35, 8
	s_add_i32 s36, s29, 0
	s_cmp_eq_u32 s17, 0
	v_mov_b32_e32 v3, s49
	v_or_b32_e32 v2, s48, v96
	s_cselect_b32 s37, 0, -2
	v_lshlrev_b64 v[2:3], 9, v[2:3]
	s_lshl_b32 s17, s33, 4
	s_lshl_b32 s40, s37, 6
	v_lshl_add_u64 v[4:5], s[58:59], 0, v[2:3]
	s_and_b32 s38, s17, 0x180
	s_add_i32 s28, s40, s28
	v_lshl_add_u64 v[4:5], v[4:5], 0, s[38:39]
	v_mov_b32_e32 v133, v93
	s_lshl_b32 s15, s15, 2
	v_lshl_add_u64 v[2:3], s[42:43], 0, v[2:3]
	v_lshl_add_u64 v[134:135], v[4:5], 0, v[132:133]
	v_mov_b32_e32 v4, s15
	v_lshl_add_u64 v[2:3], v[2:3], 0, s[38:39]
	s_ashr_i32 s29, s28, 31
	global_load_dword v18, v4, s[68:69]
	v_lshl_add_u64 v[136:137], v[2:3], 0, v[132:133]
	s_lshl_b64 s[28:29], s[28:29], 9
	v_lshl_add_u64 v[2:3], v[136:137], 0, s[28:29]
	v_lshl_add_u64 v[4:5], v[134:135], 0, s[28:29]
	global_load_dwordx4 v[182:185], v[2:3], off
	global_load_dwordx4 v[186:189], v[4:5], off
	v_lshl_add_u64 v[2:3], v[2:3], 0, s[98:99]
	v_lshl_add_u64 v[4:5], v[4:5], 0, s[98:99]
	global_load_dwordx4 v[190:193], v[2:3], off
	global_load_dwordx4 v[194:197], v[4:5], off
	v_lshl_add_u64 v[2:3], v[2:3], 0, s[98:99]
	v_lshl_add_u64 v[4:5], v[4:5], 0, s[98:99]
	global_load_dwordx4 v[208:211], v[2:3], off
	global_load_dwordx4 v[212:215], v[4:5], off
	v_lshl_add_u64 v[2:3], v[2:3], 0, s[98:99]
	v_lshl_add_u64 v[4:5], v[4:5], 0, s[98:99]
	global_load_dwordx4 v[216:219], v[2:3], off
	global_load_dwordx4 v[220:223], v[4:5], off
	s_cmp_eq_u32 s37, 0
	s_cbranch_scc1 .Lswa_ld_done
	v_lshl_add_u64 v[2:3], v[2:3], 0, s[98:99]
	v_lshl_add_u64 v[4:5], v[4:5], 0, s[98:99]
	global_load_dwordx4 v[224:227], v[2:3], off
	global_load_dwordx4 v[228:231], v[4:5], off
	v_lshl_add_u64 v[2:3], v[2:3], 0, s[98:99]
	v_lshl_add_u64 v[4:5], v[4:5], 0, s[98:99]
	global_load_dwordx4 v[232:235], v[2:3], off
	global_load_dwordx4 v[236:239], v[4:5], off
.Lswa_ld_done:
	v_add_u32_e32 v19, s16, v1
	v_mov_b32_e32 v16, v93
	v_mov_b32_e32 v17, v93
	s_waitcnt vmcnt(0)
	v_mov_b32_e32 v2, v93
	v_mov_b32_e32 v3, v93
	v_mov_b32_e32 v4, v93
	v_mov_b32_e32 v5, v93
	v_mov_b32_e32 v6, v93
	v_mov_b32_e32 v7, v93
	v_mov_b32_e32 v8, v93
	v_mov_b32_e32 v9, v93
	v_mov_b32_e32 v10, v93
	v_mov_b32_e32 v11, v93
	v_mov_b32_e32 v12, v93
	v_mov_b32_e32 v13, v93
	v_mov_b32_e32 v14, v93
	v_mov_b32_e32 v15, v93
	v_subrev_u32_e32 v150, s40, v19
	s_mov_b32 s15, 1
	v_mov_b32_e32 v152, 1.0
	v_lshl_add_u32 v131, v90, 2, s36
	v_lshl_add_u32 v133, v91, 2, s36
	s_or_b32 s16, s13, 31
	s_add_i32 s17, s13, 0xffffff81
	s_add_i32 s28, s13, 0xffffff9f
	s_sub_i32 s29, 4, s37
	s_add_i32 s33, s35, s40
	s_waitcnt vmcnt(0)
	s_and_saveexec_b64 s[50:51], s[0:1]
	v_mul_f32_e32 v204, 0x41000000, v204
	ds_write_b32 v97, v204 offset:34816
	s_or_b64 exec, exec, s[50:51]
	v_add_u32_e32 v34, 0x9000, v140
	v_add_u32_e32 v35, 0x9000, v141
	ds_write_b128 v34, v[182:185] offset:16384
	ds_write_b128 v35, v[186:189]
	v_add_u32_e32 v34, 0xb000, v140
	v_add_u32_e32 v35, 0xb000, v141
	ds_write_b128 v34, v[190:193] offset:16384
	ds_write_b128 v35, v[194:197]
	v_add_u32_e32 v34, 0x11000, v140
	v_add_u32_e32 v35, 0x11000, v141
	ds_write_b128 v34, v[208:211] offset:16384
	ds_write_b128 v35, v[212:215]
	v_add_u32_e32 v34, 0x13000, v140
	v_add_u32_e32 v35, 0x13000, v141
	ds_write_b128 v34, v[216:219] offset:16384
	ds_write_b128 v35, v[220:223]
	s_cmp_eq_u32 s37, 0
	s_cbranch_scc1 .Lswa_wr_done
	v_add_u32_e32 v34, 0x19000, v140
	v_add_u32_e32 v35, 0x19000, v141
	ds_write_b128 v34, v[224:227] offset:16384
	ds_write_b128 v35, v[228:231]
	v_add_u32_e32 v34, 0x1b000, v140
	v_add_u32_e32 v35, 0x1b000, v141
	ds_write_b128 v34, v[232:235] offset:16384
	ds_write_b128 v35, v[236:239]
.Lswa_wr_done:
	v_mul_f32_e32 v151, 0x41000000, v18
	s_waitcnt lgkmcnt(2)
	v_mov_b64_e32 v[32:33], v[16:17]
	v_mov_b64_e32 v[30:31], v[14:15]
	v_mov_b64_e32 v[28:29], v[12:13]
	v_mov_b64_e32 v[26:27], v[10:11]
	v_mov_b64_e32 v[24:25], v[8:9]
	v_mov_b64_e32 v[22:23], v[6:7]
	v_mov_b64_e32 v[20:21], v[4:5]
	v_mov_b64_e32 v[18:19], v[2:3]
	s_waitcnt lgkmcnt(0)
	s_barrier
	s_branch .LBB0_604
.LBB0_603:
	v_subrev_u32_e32 v150, 64, v150
	s_add_i32 s33, s33, 64
	s_add_i32 s15, s15, 1
	s_and_b64 vcc, exec, s[48:49]
	s_waitcnt lgkmcnt(0)
	s_cbranch_vccnz .LBB0_616

; #define LAS __attribute__((address_space(3)))
; __device__ __forceinline__ void qk64(f32x16& p0, f32x16& p1, const LAS char* kl, int r32, int hi, const bf16x8* qr) {
; #pragma unroll
;     for (int ks = 0; ks < 4; ++ks) { const LAS char* a = kl + KSWZ64(r32, 2 * ks + hi);
;         const bf16x8 b0 = *reinterpret_cast<const LAS bf16x8*>(a);
;         const bf16x8 b1 = *reinterpret_cast<const LAS bf16x8*>(a + 32 * 128);
;         p0 = __builtin_amdgcn_mfma_f32_32x32x16_bf16(b0, qr[ks], p0, 0, 0, 0);
;         p1 = __builtin_amdgcn_mfma_f32_32x32x16_bf16(b1, qr[ks], p1, 0, 0, 0); }
; }
; template <bool MLA> __device__ __forceinline__ void attn_unit(const AttnP& P, int b, int hh, int qb, LAS char* lds) {
;     ...
;     for (int t = 0; t < NT; ++t) {
;         const int buf = t & 1;
;         if (t + 1 < NT) LOADT(t + 1, buf ^ 1);
;         const int kb = kbase0 + 64 * t;
;         const bool act = (kb <= qlo + 31) && (MLA || kb + 63 >= qlo - (W - 1));
;         if (act) {
;             f32x16 p0 = f32x16{}, p1 = f32x16{};
;             if constexpr (MLA) {
; #pragma unroll
;                 for (int r = 0; r < 16; ++r) { p0[r] = -m_reg; p1[r] = -m_reg; } }
;             if constexpr (MLA) { qk_mla(p0, p1, (int)(uintptr_t)K_lds + buf * KBYTES, r32, hi, qr); }
;             else { qk64(p0, p1, K_lds + buf * KBYTES, r32, hi, qr); }
;             const int dq = qm - kb;
;             if constexpr (!MLA) {
; #pragma unroll
;                 for (int r = 0; r < 16; ++r) { const int c = (r & 3) + 8 * (r >> 2); p0[r] += bias_l[(dq - c) & 127]; p1[r] += bias_l[(dq - c - 32) & 127]; }
.LBB0_606:
	s_add_i32 s35, s15, -1
	s_lshr_b32 s100, s35, 1
	s_lshl_b32 s100, s100, 15
	s_and_b32 s35, s35, 1
	s_lshl_b32 s101, s35, 13
	s_add_i32 s100, s100, s101
	s_add_i32 s100, s100, 0x9000
	s_cmp_le_i32 s33, s16
	s_cselect_b64 s[36:37], -1, 0
	s_add_i32 s57, s33, 63
	s_cmp_ge_i32 s57, s17
	s_cselect_b64 s[40:41], -1, 0
	s_and_b64 s[36:37], s[36:37], s[40:41]
	s_andn2_b64 vcc, exec, s[36:37]
	s_cbranch_vccnz .LBB0_614
	s_mov_b32 s38, s100
	v_add_u32_e32 v42, s38, v142
	v_add_u32_e32 v38, v42, v143
	ds_read_b128 v[34:37], v38 offset:16384
	ds_read_b128 v[38:41], v38 offset:20480
	v_add_u32_e32 v138, v42, v144
	ds_read_b128 v[154:157], v138 offset:16384
	v_add_u32_e32 v153, 59, v150
	s_waitcnt lgkmcnt(2)
	v_mfma_f32_32x32x16_bf16 v[50:65], v[34:37], v[66:69], 0
	v_add_u32_e32 v139, v42, v145
	v_add_u32_e32 v163, v42, v146
	v_and_b32_e32 v158, 0x7f, v153
	v_lshl_add_u32 v180, v158, 2, 0
	ds_read_b128 v[158:161], v138 offset:20480
	ds_read_b128 v[164:167], v139 offset:16384
	ds_read_b128 v[168:171], v139 offset:20480
	ds_read_b128 v[172:175], v163 offset:16384
	ds_read_b128 v[176:179], v163 offset:20480
	v_add_u32_e32 v138, 0x9b, v150
	v_and_b32_e32 v138, 0x7f, v138
	s_waitcnt lgkmcnt(6)
	v_mfma_f32_32x32x16_bf16 v[34:49], v[38:41], v[66:69], 0
	v_lshl_add_u32 v139, v138, 2, 0
	v_add_u32_e32 v138, 0xba, v150
	v_and_b32_e32 v138, 0x7f, v138
	v_add_u32_e32 v163, 0xb2, v150
	v_and_b32_e32 v163, 0x7f, v163
	v_lshl_add_u32 v163, v163, 2, 0
	v_add_u32_e32 v181, 0x81, v150
	s_waitcnt lgkmcnt(5)
	v_mfma_f32_32x32x16_bf16 v[50:65], v[154:157], v[70:73], v[50:65]
	v_lshl_add_u32 v155, v138, 2, 0
	v_add_u32_e32 v138, 0x9a, v150
	v_and_b32_e32 v138, 0x7f, v138
	v_lshl_add_u32 v156, v138, 2, 0
	v_add_u32_e32 v138, 0xb9, v150
	v_and_b32_e32 v138, 0x7f, v138
	v_lshl_add_u32 v157, v138, 2, 0
	s_waitcnt lgkmcnt(4)
	v_mfma_f32_32x32x16_bf16 v[34:49], v[158:161], v[70:73], v[34:49]
	v_add_u32_e32 v138, 0x99, v150
	v_and_b32_e32 v138, 0x7f, v138
	v_lshl_add_u32 v158, v138, 2, 0
	v_add_u32_e32 v138, 0xb8, v150
	v_and_b32_e32 v138, 0x7f, v138
	v_lshl_add_u32 v159, v138, 2, 0
	v_add_u32_e32 v138, 0x98, v150
	s_waitcnt lgkmcnt(3)
	v_mfma_f32_32x32x16_bf16 v[50:65], v[164:167], v[74:77], v[50:65]
	v_add_u32_e32 v164, 0x92, v150
	v_and_b32_e32 v164, 0x7f, v164
	v_lshl_add_u32 v165, v164, 2, 0
	v_add_u32_e32 v164, 0xb1, v150
	v_and_b32_e32 v164, 0x7f, v164
	v_lshl_add_u32 v166, v164, 2, 0
	v_add_u32_e32 v164, 0x91, v150
	v_and_b32_e32 v164, 0x7f, v164
	v_and_b32_e32 v138, 0x7f, v138
	v_lshl_add_u32 v167, v164, 2, 0
	v_add_u32_e32 v164, 0xb0, v150
	v_lshl_add_u32 v160, v138, 2, 0
	v_and_b32_e32 v164, 0x7f, v164
	s_waitcnt lgkmcnt(2)
	v_mfma_f32_32x32x16_bf16 v[34:49], v[168:171], v[74:77], v[34:49]
	ds_read_b32 v138, v180 offset:34816
	ds_read_b32 v154, v139 offset:34816
	ds_read_b32 v139, v155 offset:34816
	ds_read_b32 v155, v156 offset:34816
	ds_read_b32 v156, v157 offset:34816
	ds_read_b32 v158, v158 offset:34816
	ds_read_b32 v157, v159 offset:34816
	ds_read_b32 v159, v160 offset:34816
	v_add_u32_e32 v160, 0xb3, v150
	v_add_u32_e32 v161, 0x93, v150
	v_lshl_add_u32 v169, v164, 2, 0
	v_add_u32_e32 v164, 0x90, v150
	v_and_b32_e32 v160, 0x7f, v160
	v_and_b32_e32 v161, 0x7f, v161
	v_and_b32_e32 v164, 0x7f, v164
	v_lshl_add_u32 v160, v160, 2, 0
	v_lshl_add_u32 v161, v161, 2, 0
	v_lshl_add_u32 v170, v164, 2, 0
	ds_read_b32 v160, v160 offset:34816
	ds_read_b32 v164, v161 offset:34816
	ds_read_b32 v161, v163 offset:34816
	ds_read_b32 v165, v165 offset:34816
	ds_read_b32 v166, v166 offset:34816
	ds_read_b32 v168, v167 offset:34816
	ds_read_b32 v167, v169 offset:34816
	ds_read_b32 v169, v170 offset:34816
	v_add_u32_e32 v170, 0x8b, v150
	v_and_b32_e32 v170, 0x7f, v170
	v_lshl_add_u32 v171, v170, 2, 0
	v_add_u32_e32 v170, 0xaa, v150
	v_and_b32_e32 v170, 0x7f, v170
	s_waitcnt lgkmcnt(14)
	v_mfma_f32_32x32x16_bf16 v[50:65], v[172:175], v[78:81], v[50:65]
	v_lshl_add_u32 v173, v170, 2, 0
	v_add_u32_e32 v170, 0x8a, v150
	v_and_b32_e32 v170, 0x7f, v170
	v_lshl_add_u32 v174, v170, 2, 0
	v_add_u32_e32 v170, 0xa9, v150
	v_and_b32_e32 v170, 0x7f, v170
	v_lshl_add_u32 v175, v170, 2, 0
	v_add_u32_e32 v170, 0x89, v150
	v_and_b32_e32 v170, 0x7f, v170
	v_mfma_f32_32x32x16_bf16 v[34:49], v[176:179], v[78:81], v[34:49]
	v_lshl_add_u32 v176, v170, 2, 0
	v_add_u32_e32 v170, 0xa8, v150
	v_and_b32_e32 v170, 0x7f, v170
	v_add_u32_e32 v163, 0xab, v150
	v_lshl_add_u32 v177, v170, 2, 0
	v_add_u32_e32 v170, 0x88, v150
	v_and_b32_e32 v163, 0x7f, v163
	v_and_b32_e32 v170, 0x7f, v170
	v_add_u32_e32 v180, 0x82, v150
	v_lshl_add_u32 v163, v163, 2, 0
	v_lshl_add_u32 v178, v170, 2, 0
	v_and_b32_e32 v180, 0x7f, v180
	v_and_b32_e32 v181, 0x7f, v181
	ds_read_b32 v170, v163 offset:34816
	ds_read_b32 v172, v171 offset:34816
	ds_read_b32 v171, v173 offset:34816
	ds_read_b32 v173, v174 offset:34816
	ds_read_b32 v174, v175 offset:34816
	ds_read_b32 v176, v176 offset:34816
	ds_read_b32 v175, v177 offset:34816
	ds_read_b32 v177, v178 offset:34816
	v_add_u32_e32 v163, 0xa3, v150
	v_add_u32_e32 v178, 0x83, v150
	v_add_u32_e32 v179, 0xa2, v150
	v_lshl_add_u32 v182, v180, 2, 0
	v_add_u32_e32 v180, 0xa1, v150
	v_lshl_add_u32 v183, v181, 2, 0
	v_add_u32_e32 v181, 0xa0, v150
	v_and_b32_e32 v163, 0x7f, v163
	v_and_b32_e32 v178, 0x7f, v178
	v_and_b32_e32 v179, 0x7f, v179
	v_and_b32_e32 v180, 0x7f, v180
	v_and_b32_e32 v181, 0x7f, v181
	s_waitcnt lgkmcnt(14)
	v_pk_add_f32 v[50:51], v[50:51], v[138:139]
	v_add_u32_e32 v138, 0x80, v150
	v_lshl_add_u32 v163, v163, 2, 0
	v_lshl_add_u32 v178, v178, 2, 0
	v_lshl_add_u32 v179, v179, 2, 0
	v_lshl_add_u32 v180, v180, 2, 0
	v_lshl_add_u32 v181, v181, 2, 0
	v_and_b32_e32 v138, 0x7f, v138
	v_lshl_add_u32 v184, v138, 2, 0
	ds_read_b32 v138, v163 offset:34816
	ds_read_b32 v178, v178 offset:34816
	ds_read_b32 v180, v180 offset:34816
	ds_read_b32 v181, v181 offset:34816
	ds_read_b32 v139, v179 offset:34816
	ds_read_b32 v179, v182 offset:34816
	ds_read_b32 v182, v183 offset:34816
	ds_read_b32 v183, v184 offset:34816
	s_cmp_le_i32 s57, s13
	s_cselect_b64 s[36:37], -1, 0
	s_cmp_gt_i32 s33, s28
	s_cselect_b64 s[40:41], -1, 0
	s_and_b64 s[36:37], s[36:37], s[40:41]
	s_waitcnt lgkmcnt(4)
	v_pk_add_f32 v[64:65], v[64:65], v[180:181]
	s_waitcnt lgkmcnt(3)
	v_pk_add_f32 v[62:63], v[62:63], v[138:139]
	v_pk_add_f32 v[60:61], v[60:61], v[174:175]
	v_pk_add_f32 v[58:59], v[58:59], v[170:171]
	v_pk_add_f32 v[56:57], v[56:57], v[166:167]
	v_pk_add_f32 v[54:55], v[54:55], v[160:161]
	v_pk_add_f32 v[138:139], v[52:53], v[156:157]
	v_pk_add_f32 v[52:53], v[34:35], v[154:155]
	s_waitcnt lgkmcnt(0)
	v_pk_add_f32 v[34:35], v[48:49], v[182:183]
	v_pk_add_f32 v[46:47], v[46:47], v[178:179]
	v_pk_add_f32 v[44:45], v[44:45], v[176:177]
	v_pk_add_f32 v[42:43], v[42:43], v[172:173]
	v_pk_add_f32 v[40:41], v[40:41], v[168:169]
	v_pk_add_f32 v[38:39], v[38:39], v[164:165]
	v_pk_add_f32 v[36:37], v[36:37], v[158:159]
	s_and_b64 vcc, exec, s[36:37]
	s_cbranch_vccnz .LBB0_609
; __device__ __forceinline__ void mask_tile(f32x16& p0, f32x16& p1, int dq, unsigned W) {
;     const float NEG = -__builtin_inff();
; #pragma unroll
;     for (int r = 0; r < 16; ++r) { const int c = (r & 3) + 8 * (r >> 2);
;         if ((unsigned)(dq - c) >= W) p0[r] = NEG;
;         if ((unsigned)(dq - c - 32) >= W) p1[r] = NEG; }
; }
; template <bool MLA> __device__ __forceinline__ void attn_unit(const AttnP& P, int b, int hh, int qb, LAS char* lds) {
;     ...
;             if (kb + 63 > qlo || (!MLA && kb <= qlo + 31 - W)) mask_tile(p0, p1, dq, (unsigned)W);
	v_cmp_gt_u32_e32 vcc, s8, v153
	v_add_u32_e32 v48, 27, v150
	s_nop 0
	v_cndmask_b32_e32 v50, v148, v50, vcc
	v_cmp_gt_u32_e32 vcc, s8, v48
	v_add_u32_e32 v48, 58, v150
	s_nop 0
	v_cndmask_b32_e32 v52, v148, v52, vcc
	v_cmp_gt_u32_e32 vcc, s8, v48
	v_add_u32_e32 v48, 26, v150
	s_nop 0
	v_cndmask_b32_e32 v51, v148, v51, vcc
	v_cmp_gt_u32_e32 vcc, s8, v48
	v_add_u32_e32 v48, 57, v150
	s_nop 0
	v_cndmask_b32_e32 v53, v148, v53, vcc
	v_cmp_gt_u32_e32 vcc, s8, v48
	v_add_u32_e32 v48, 25, v150
	s_nop 0
	v_cndmask_b32_e32 v138, v148, v138, vcc
	v_cmp_gt_u32_e32 vcc, s8, v48
	v_add_u32_e32 v48, 56, v150
	s_nop 0
	v_cndmask_b32_e32 v36, v148, v36, vcc
	v_cmp_gt_u32_e32 vcc, s8, v48
	v_add_u32_e32 v48, 24, v150
	s_nop 0
	v_cndmask_b32_e32 v139, v148, v139, vcc
	v_cmp_gt_u32_e32 vcc, s8, v48
	v_add_u32_e32 v48, 51, v150
	s_nop 0
	v_cndmask_b32_e32 v37, v148, v37, vcc
	v_cmp_gt_u32_e32 vcc, s8, v48
	v_add_u32_e32 v48, 19, v150
	s_nop 0
	v_cndmask_b32_e32 v54, v148, v54, vcc
	v_cmp_gt_u32_e32 vcc, s8, v48
	v_add_u32_e32 v48, 50, v150
	s_nop 0
	v_cndmask_b32_e32 v38, v148, v38, vcc
	v_cmp_gt_u32_e32 vcc, s8, v48
	v_add_u32_e32 v48, 18, v150
	s_nop 0
	v_cndmask_b32_e32 v55, v148, v55, vcc
	v_cmp_gt_u32_e32 vcc, s8, v48
	v_add_u32_e32 v48, 49, v150
	s_nop 0
	v_cndmask_b32_e32 v39, v148, v39, vcc
	v_cmp_gt_u32_e32 vcc, s8, v48
	v_add_u32_e32 v48, 17, v150
	s_nop 0
	v_cndmask_b32_e32 v56, v148, v56, vcc
	v_cmp_gt_u32_e32 vcc, s8, v48
	v_add_u32_e32 v48, 48, v150
	s_nop 0
	v_cndmask_b32_e32 v40, v148, v40, vcc
	v_cmp_gt_u32_e32 vcc, s8, v48
	v_add_u32_e32 v48, 16, v150
	s_nop 0
	v_cndmask_b32_e32 v57, v148, v57, vcc
	v_cmp_gt_u32_e32 vcc, s8, v48
	v_add_u32_e32 v48, 43, v150
	s_nop 0
	v_cndmask_b32_e32 v41, v148, v41, vcc
	v_cmp_gt_u32_e32 vcc, s8, v48
	v_add_u32_e32 v48, 11, v150
	s_nop 0
	v_cndmask_b32_e32 v58, v148, v58, vcc
	v_cmp_gt_u32_e32 vcc, s8, v48
	v_add_u32_e32 v48, 42, v150
	s_nop 0
	v_cndmask_b32_e32 v42, v148, v42, vcc
	v_cmp_gt_u32_e32 vcc, s8, v48
	v_add_u32_e32 v48, 10, v150
	s_nop 0
	v_cndmask_b32_e32 v59, v148, v59, vcc
	v_cmp_gt_u32_e32 vcc, s8, v48
	v_add_u32_e32 v48, 41, v150
	s_nop 0
	v_cndmask_b32_e32 v43, v148, v43, vcc
	v_cmp_gt_u32_e32 vcc, s8, v48
	v_add_u32_e32 v48, 9, v150
	s_nop 0
	v_cndmask_b32_e32 v60, v148, v60, vcc
	v_cmp_gt_u32_e32 vcc, s8, v48
	v_add_u32_e32 v48, 40, v150
	s_nop 0
	v_cndmask_b32_e32 v44, v148, v44, vcc
	v_cmp_gt_u32_e32 vcc, s8, v48
	v_add_u32_e32 v48, 8, v150
	s_nop 0
	v_cndmask_b32_e32 v61, v148, v61, vcc
	v_cmp_gt_u32_e32 vcc, s8, v48
	v_add_u32_e32 v48, 35, v150
	s_nop 0
	v_cndmask_b32_e32 v45, v148, v45, vcc
	v_cmp_gt_u32_e32 vcc, s8, v48
	v_add_u32_e32 v48, 3, v150
	s_nop 0
	v_cndmask_b32_e32 v62, v148, v62, vcc
	v_cmp_gt_u32_e32 vcc, s8, v48
	v_add_u32_e32 v48, 34, v150
	s_nop 0
	v_cndmask_b32_e32 v46, v148, v46, vcc
	v_cmp_gt_u32_e32 vcc, s8, v48
	v_add_u32_e32 v48, 2, v150
	s_nop 0
	v_cndmask_b32_e32 v63, v148, v63, vcc
	v_cmp_gt_u32_e32 vcc, s8, v48
	v_add_u32_e32 v48, 33, v150
	s_nop 0
	v_cndmask_b32_e32 v47, v148, v47, vcc
	v_cmp_gt_u32_e32 vcc, s8, v48
	v_add_u32_e32 v48, 1, v150
	s_nop 0
	v_cndmask_b32_e32 v64, v148, v64, vcc
	v_cmp_gt_u32_e32 vcc, s8, v48
	v_add_u32_e32 v48, 32, v150
	s_nop 0
	v_cndmask_b32_e32 v34, v148, v34, vcc
	v_cmp_gt_u32_e32 vcc, s8, v48
	s_nop 1
	v_cndmask_b32_e32 v65, v148, v65, vcc
	v_cmp_gt_u32_e32 vcc, s8, v150
	s_nop 1
	v_cndmask_b32_e32 v35, v148, v35, vcc

; #define WRITET(bf) do { if constexpr (!MLA) { *(LAS bf16x8*)(K_lds + (bf) * KBYTES + kws) = sk0; *(LAS bf16x8*)(V_lds + (bf) * VBYTES + vst0) = sv0; } } while (0)
; template <bool MLA> __device__ __forceinline__ void attn_unit(const AttnP& P, int b, int hh, int qb, LAS char* lds) {
;     ...
;         if (t + 1 < NT) { asm volatile("s_waitcnt vmcnt(0)" ::: "memory"); WRITET(buf ^ 1); }
;         __syncthreads();
.LBB0_614:
	s_branch .LBB0_603

; #define LAS __attribute__((address_space(3)))
; __global__ void __launch_bounds__(512) fwd_mega(Args a) {
;     extern __shared__ __attribute__((aligned(16))) unsigned char lds_raw[];
;     LAS unsigned char* lds = (LAS unsigned char*)lds_raw;
;     cg::grid_group grid = cg::this_grid();
;     const int tid = threadIdx.x, lane = tid & 63, wave = __builtin_amdgcn_readfirstlane(tid >> 6);
	.amdhsa_kernel _Z8fwd_mega4Args
		.amdhsa_group_segment_fixed_size 0
		.amdhsa_private_segment_fixed_size 0
		.amdhsa_kernarg_size 432
		.amdhsa_user_sgpr_count 2
		.amdhsa_user_sgpr_dispatch_ptr 0
		.amdhsa_user_sgpr_queue_ptr 0
		.amdhsa_user_sgpr_kernarg_segment_ptr 1
		.amdhsa_user_sgpr_dispatch_id 0
		.amdhsa_user_sgpr_kernarg_preload_length 0
		.amdhsa_user_sgpr_kernarg_preload_offset 0
		.amdhsa_user_sgpr_private_segment_size 0
		.amdhsa_uses_dynamic_stack 0
		.amdhsa_enable_private_segment 0
		.amdhsa_system_sgpr_workgroup_id_x 1
		.amdhsa_system_sgpr_workgroup_id_y 0
		.amdhsa_system_sgpr_workgroup_id_z 0
		.amdhsa_system_sgpr_workgroup_info 0
		.amdhsa_system_vgpr_workitem_id 2
		.amdhsa_next_free_vgpr 256
		.amdhsa_next_free_sgpr 102
		.amdhsa_accum_offset 256
		.amdhsa_reserve_vcc 1
		.amdhsa_float_round_mode_32 0
		.amdhsa_float_round_mode_16_64 0
		.amdhsa_float_denorm_mode_32 3
		.amdhsa_float_denorm_mode_16_64 3
		.amdhsa_dx10_clamp 1
		.amdhsa_ieee_mode 1
		.amdhsa_fp16_overflow 0
		.amdhsa_tg_split 0
		.amdhsa_exception_fp_ieee_invalid_op 0
		.amdhsa_exception_fp_denorm_src 0
		.amdhsa_exception_fp_ieee_div_zero 0
		.amdhsa_exception_fp_ieee_overflow 0
		.amdhsa_exception_fp_ieee_underflow 0
		.amdhsa_exception_fp_ieee_inexact 0
		.amdhsa_exception_int_div_zero 0
	.end_amdhsa_kernel

; #define LAS __attribute__((address_space(3)))
; __global__ void __launch_bounds__(512) fwd_mega(Args a) {
;     extern __shared__ __attribute__((aligned(16))) unsigned char lds_raw[];
;     LAS unsigned char* lds = (LAS unsigned char*)lds_raw;
;     cg::grid_group grid = cg::this_grid();
;     const int tid = threadIdx.x, lane = tid & 63, wave = __builtin_amdgcn_readfirstlane(tid >> 6);
amdhsa.kernels:
  - .agpr_count:     0
    .args:
      - .offset:         0
        .size:           176
        .value_kind:     by_value
      - .offset:         176
        .size:           4
        .value_kind:     hidden_block_count_x
      - .offset:         180
        .size:           4
        .value_kind:     hidden_block_count_y
      - .offset:         184
        .size:           4
        .value_kind:     hidden_block_count_z
      - .offset:         188
        .size:           2
        .value_kind:     hidden_group_size_x
      - .offset:         190
        .size:           2
        .value_kind:     hidden_group_size_y
      - .offset:         192
        .size:           2
        .value_kind:     hidden_group_size_z
      - .offset:         194
        .size:           2
        .value_kind:     hidden_remainder_x
      - .offset:         196
        .size:           2
        .value_kind:     hidden_remainder_y
      - .offset:         198
        .size:           2
        .value_kind:     hidden_remainder_z
      - .offset:         216
        .size:           8
        .value_kind:     hidden_global_offset_x
      - .offset:         224
        .size:           8
        .value_kind:     hidden_global_offset_y
      - .offset:         232
        .size:           8
        .value_kind:     hidden_global_offset_z
      - .offset:         240
        .size:           2
        .value_kind:     hidden_grid_dims
      - .offset:         264
        .size:           8
        .value_kind:     hidden_multigrid_sync_arg
      - .offset:         296
        .size:           4
        .value_kind:     hidden_dynamic_lds_size
    .group_segment_fixed_size: 0
    .kernarg_segment_align: 8
    .kernarg_segment_size: 432
    .language:       OpenCL C
    .language_version:
      - 2
      - 0
    .max_flat_workgroup_size: 512
    .name:           _Z8fwd_mega4Args
    .private_segment_fixed_size: 0
    .sgpr_count:     108
    .sgpr_spill_count: 51
    .symbol:         _Z8fwd_mega4Args.kd
    .uniform_work_group_size: 1
    .uses_dynamic_stack: false
    .vgpr_count:     256
    .vgpr_spill_count: 0
    .wavefront_size: 64
